# v_m6 + scan loop: y-store address advanced incrementally (1 VALU + SALU per chunk instead of 6 VALU + 4 SALU)
# baseline (speedup 1.0000x reference)
; DI void scan_item(const Params& p, int item, char* smem) {
;     ...
;   u16* yb = p.yscan + ((long)dir * MH + (long)bb * T) * 256 + hd * 64 + rg * 16;
;   auto tof = [&](int s) { return dir == 0 ? s : (s < 256 ? 255 - s : 4607 - s); };
;     ...
;   auto ldstep = [&](const float* b) {
;     StepIn x;
;     x.r = *(const f32x4v*)(b + cg4); x.k = *(const f32x4v*)(b + 64 + cg4); x.v = b[voff];
;     x.w = *(const f32x4v*)(b + 192 + cg4); x.d = *(const f32x4v*)(b + 256 + cg4); x.b = *(const f32x4v*)(b + 320 + cg4);
;     return x;
;   };
;   for (int ci = 0; ci < nch; ci++) {
;     if (ci + 1 < nch) gload(ci + 1);
;     const float* base = sIn + (ci & 1) * 16 * 6 * 64;
;     float ykeep = 0.f;
;     StepIn cur = ldstep(base);
; #pragma unroll
;     for (int st = 0; st < 16; st++) {
;       StepIn nxt = cur;
;       if (st + 1 < 16) nxt = ldstep(base + (st + 1) * 6 * 64);
;       __builtin_amdgcn_sched_barrier(0);
;       f32x2 ra = {cur.r.x, cur.r.y}, rb = {cur.r.z, cur.r.w}, ka = {cur.k.x, cur.k.y}, kb = {cur.k.z, cur.k.w};
;       f32x2 wa = {cur.w.x, cur.w.y}, wb = {cur.w.z, cur.w.w}, da = {cur.d.x, cur.d.y}, db = {cur.d.z, cur.d.w};
;       f32x2 ba = {cur.b.x, cur.b.y}, bb2 = {cur.b.z, cur.b.w};
;       f32x2 pp = Sa * ka + Sb * kb;
;       float sa = allreduce16(pp.x + pp.y);
;       f32x2 vv2 = {cur.v, cur.v};
;       f32x2 sa2 = {sa, sa};
;       Sa = (Sa * wa + vv2 * da) - sa2 * ba;
;       Sb = (Sb * wb + vv2 * db) - sa2 * bb2;
;       f32x2 yy = Sa * ra + Sb * rb;
;       float y = allreduce16(yy.x + yy.y);
;       ykeep = (l16 == st) ? y : ykeep;
;       cur = nxt;
;     }
.LBB0_398:
	v_lshlrev_b32_e32 v49, 2, v37
	v_lshlrev_b32_e32 v50, 2, v41
	v_mad_u32_u24 v32, v13, 6, v12
	v_mad_u32_u24 v33, v17, 6, v16
	v_mad_u32_u24 v34, v21, 6, v20
	v_lshl_or_b32 v32, v32, 8, v38
	v_lshl_or_b32 v33, v33, 8, v39
	v_lshl_or_b32 v34, v34, 8, v40
	s_movk_i32 s72, 0x10
	v_add_u32_e32 v0, s72, v13
	v_add_u32_e32 v4, s72, v17
	v_add_u32_e32 v8, s72, v21
	v_cmp_lt_i32_e32 vcc, 0xff, v0
	s_nop 1
	v_cndmask_b32_e32 v1, v208, v209, vcc
	v_cmp_lt_i32_e32 vcc, 0xff, v4
	v_sub_u32_e32 v1, v1, v0
	v_cndmask_b32_e64 v0, v1, v0, s[36:37]
	v_cndmask_b32_e32 v5, v208, v209, vcc
	v_cmp_lt_i32_e32 vcc, 0xff, v8
	v_sub_u32_e32 v5, v5, v4
	v_cndmask_b32_e64 v4, v5, v4, s[36:37]
	v_cndmask_b32_e32 v9, v208, v209, vcc
	v_sub_u32_e32 v9, v9, v8
	v_cndmask_b32_e64 v8, v9, v8, s[36:37]
	v_mad_i64_i32 v[0:1], s[12:13], v0, 9, v[14:15]
	v_mad_i64_i32 v[4:5], s[12:13], v4, 9, v[18:19]
	v_mad_i64_i32 v[8:9], s[12:13], v8, 9, v[22:23]
	v_lshlrev_b64 v[0:1], 7, v[0:1]
	v_lshlrev_b64 v[4:5], 7, v[4:5]
	v_lshlrev_b64 v[8:9], 7, v[8:9]
	v_lshl_add_u64 v[0:1], v[24:25], 0, v[0:1]
	v_lshl_add_u64 v[4:5], v[26:27], 0, v[4:5]
	v_lshl_add_u64 v[8:9], v[28:29], 0, v[8:9]
	v_mov_b64_e32 v[236:237], v[0:1]
	v_mov_b64_e32 v[238:239], v[4:5]
	v_mov_b64_e32 v[240:241], v[8:9]
	global_load_dwordx4 v[0:3], v[236:237], off
	global_load_dwordx4 v[4:7], v[238:239], off
	global_load_dwordx4 v[8:11], v[240:241], off
	v_sub_u32_e32 v243, 0xff, v36
	v_cndmask_b32_e64 v242, v243, v36, s[36:37]
	v_mov_b32_e32 v243, 0
	v_lshlrev_b64 v[242:243], 9, v[242:243]
	v_lshl_add_u64 v[242:243], v[30:31], 0, v[242:243]
	s_mov_b32 s26, 0
.Lscan_loop:
	ds_read_b128 v[72:75], v49 offset:256
	ds_read_b32 v88, v50 offset:512
	ds_read_b128 v[80:83], v49 offset:1024
	ds_read_b128 v[76:79], v49 offset:768
	ds_read_b128 v[84:87], v49 offset:1280
	ds_read_b128 v[68:71], v49
	ds_read_b128 v[100:103], v49 offset:1792
	ds_read_b32 v116, v50 offset:2048
	ds_read_b128 v[108:111], v49 offset:2560
	ds_read_b128 v[104:107], v49 offset:2304
	ds_read_b128 v[112:115], v49 offset:2816
	ds_read_b128 v[96:99], v49 offset:1536
	s_add_i32 s72, s26, 32
	s_mov_b32 vcc_hi, 0x4c3800
	s_cmp_eq_u32 s72, 0x100
	s_cselect_b32 vcc_lo, vcc_hi, 0xffffb800
	s_cmp_lg_u32 s36, 0
	s_cselect_b32 vcc_lo, 0x4800, vcc_lo
	s_cmp_ge_u32 s72, 0x1100
	s_cselect_b32 vcc_lo, 0, vcc_lo
	s_ashr_i32 vcc_hi, vcc_lo, 31
	v_lshl_add_u64 v[236:237], v[236:237], 0, vcc
	v_lshl_add_u64 v[238:239], v[238:239], 0, vcc
	v_lshl_add_u64 v[240:241], v[240:241], 0, vcc
	global_load_dwordx4 v[162:165], v[236:237], off
	global_load_dwordx4 v[166:169], v[238:239], off
	global_load_dwordx4 v[170:173], v[240:241], off
	s_waitcnt lgkmcnt(6)
	ds_read_b128 v[122:125], v49 offset:3328
	ds_read_b32 v138, v50 offset:3584
	ds_read_b128 v[130:133], v49 offset:4096
	ds_read_b128 v[126:129], v49 offset:3840
	ds_read_b128 v[134:137], v49 offset:4352
	ds_read_b128 v[118:121], v49 offset:3072
	v_pk_mul_f32 v[56:57], v[90:91], v[72:73]
	v_pk_mul_f32 v[60:61], v[88:89], v[80:81] op_sel_hi:[0,1]
	v_pk_fma_f32 v[56:57], v[92:93], v[74:75], v[56:57]
	v_pk_mul_f32 v[62:63], v[88:89], v[82:83] op_sel_hi:[0,1]
	v_add_f32_e32 v58, v56, v57
	v_pk_fma_f32 v[60:61], v[90:91], v[76:77], v[60:61]
	v_pk_fma_f32 v[62:63], v[92:93], v[78:79], v[62:63]
	v_add_f32_dpp v58, v58, v58 quad_perm:[1,0,3,2] row_mask:0xf bank_mask:0xf bound_ctrl:1
	s_nop 1
	v_add_f32_dpp v58, v58, v58 quad_perm:[2,3,0,1] row_mask:0xf bank_mask:0xf bound_ctrl:1
	s_nop 1
	v_add_f32_dpp v58, v58, v58 row_half_mirror row_mask:0xf bank_mask:0xf bound_ctrl:1
	s_nop 1
	v_add_f32_dpp v58, v58, v58 row_mirror row_mask:0xf bank_mask:0xf bound_ctrl:1
	s_nop 0
	v_pk_fma_f32 v[90:91], v[84:85], v[58:59], v[60:61] op_sel_hi:[1,0,1] neg_lo:[1,0,0] neg_hi:[1,0,0]
	v_pk_fma_f32 v[92:93], v[86:87], v[58:59], v[62:63] op_sel_hi:[1,0,1] neg_lo:[1,0,0] neg_hi:[1,0,0]
	s_waitcnt lgkmcnt(6)
	ds_read_b128 v[144:147], v49 offset:4864
	ds_read_b32 v160, v50 offset:5120
	ds_read_b128 v[152:155], v49 offset:5632
	ds_read_b128 v[148:151], v49 offset:5376
	ds_read_b128 v[156:159], v49 offset:5888
	ds_read_b128 v[140:143], v49 offset:4608
	v_pk_mul_f32 v[56:57], v[90:91], v[100:101]
	v_pk_mul_f32 v[64:65], v[70:71], v[92:93]
	v_pk_fma_f32 v[56:57], v[92:93], v[102:103], v[56:57]
	v_pk_fma_f32 v[64:65], v[68:69], v[90:91], v[64:65]
	v_add_f32_e32 v58, v56, v57
	v_add_f32_e32 v66, v64, v65
	v_pk_mul_f32 v[60:61], v[116:117], v[108:109] op_sel_hi:[0,1]
	v_add_f32_dpp v58, v58, v58 quad_perm:[1,0,3,2] row_mask:0xf bank_mask:0xf bound_ctrl:1
	v_add_f32_dpp v66, v66, v66 quad_perm:[1,0,3,2] row_mask:0xf bank_mask:0xf bound_ctrl:1
	v_pk_fma_f32 v[60:61], v[90:91], v[104:105], v[60:61]
	v_add_f32_dpp v58, v58, v58 quad_perm:[2,3,0,1] row_mask:0xf bank_mask:0xf bound_ctrl:1
	v_add_f32_dpp v66, v66, v66 quad_perm:[2,3,0,1] row_mask:0xf bank_mask:0xf bound_ctrl:1
	v_pk_mul_f32 v[62:63], v[116:117], v[110:111] op_sel_hi:[0,1]
	v_add_f32_dpp v58, v58, v58 row_half_mirror row_mask:0xf bank_mask:0xf bound_ctrl:1
	v_add_f32_dpp v66, v66, v66 row_half_mirror row_mask:0xf bank_mask:0xf bound_ctrl:1
	v_pk_fma_f32 v[62:63], v[92:93], v[106:107], v[62:63]
	v_add_f32_dpp v58, v58, v58 row_mirror row_mask:0xf bank_mask:0xf bound_ctrl:1
	v_add_f32_dpp v66, v66, v66 row_mirror row_mask:0xf bank_mask:0xf bound_ctrl:1
	v_pk_fma_f32 v[90:91], v[112:113], v[58:59], v[60:61] op_sel_hi:[1,0,1] neg_lo:[1,0,0] neg_hi:[1,0,0]
	v_pk_fma_f32 v[92:93], v[114:115], v[58:59], v[62:63] op_sel_hi:[1,0,1] neg_lo:[1,0,0] neg_hi:[1,0,0]
	v_cndmask_b32_e64 v67, 0, v66, s[38:39]
	s_waitcnt lgkmcnt(6)
; DI void scan_item(const Params& p, int item, char* smem) {
;     ...
;     for (int st = 0; st < 16; st++) {
;       StepIn nxt = cur;
;       if (st + 1 < 16) nxt = ldstep(base + (st + 1) * 6 * 64);
;       __builtin_amdgcn_sched_barrier(0);
;       f32x2 ra = {cur.r.x, cur.r.y}, rb = {cur.r.z, cur.r.w}, ka = {cur.k.x, cur.k.y}, kb = {cur.k.z, cur.k.w};
;       f32x2 wa = {cur.w.x, cur.w.y}, wb = {cur.w.z, cur.w.w}, da = {cur.d.x, cur.d.y}, db = {cur.d.z, cur.d.w};
;       f32x2 ba = {cur.b.x, cur.b.y}, bb2 = {cur.b.z, cur.b.w};
;       f32x2 pp = Sa * ka + Sb * kb;
;       float sa = allreduce16(pp.x + pp.y);
;       f32x2 vv2 = {cur.v, cur.v};
;       f32x2 sa2 = {sa, sa};
;       Sa = (Sa * wa + vv2 * da) - sa2 * ba;
;       Sb = (Sb * wb + vv2 * db) - sa2 * bb2;
;       f32x2 yy = Sa * ra + Sb * rb;
;       float y = allreduce16(yy.x + yy.y);
;       ykeep = (l16 == st) ? y : ykeep;
;       cur = nxt;
;     }
	ds_read_b128 v[72:75], v49 offset:6400
	ds_read_b32 v88, v50 offset:6656
	ds_read_b128 v[80:83], v49 offset:7168
	ds_read_b128 v[76:79], v49 offset:6912
	ds_read_b128 v[84:87], v49 offset:7424
	ds_read_b128 v[68:71], v49 offset:6144
	v_pk_mul_f32 v[56:57], v[90:91], v[122:123]
	v_pk_mul_f32 v[64:65], v[98:99], v[92:93]
	v_pk_fma_f32 v[56:57], v[92:93], v[124:125], v[56:57]
	v_pk_fma_f32 v[64:65], v[96:97], v[90:91], v[64:65]
	v_add_f32_e32 v58, v56, v57
	v_add_f32_e32 v66, v64, v65
	v_pk_mul_f32 v[60:61], v[138:139], v[130:131] op_sel_hi:[0,1]
	v_add_f32_dpp v58, v58, v58 quad_perm:[1,0,3,2] row_mask:0xf bank_mask:0xf bound_ctrl:1
	v_add_f32_dpp v66, v66, v66 quad_perm:[1,0,3,2] row_mask:0xf bank_mask:0xf bound_ctrl:1
	v_pk_fma_f32 v[60:61], v[90:91], v[126:127], v[60:61]
	v_add_f32_dpp v58, v58, v58 quad_perm:[2,3,0,1] row_mask:0xf bank_mask:0xf bound_ctrl:1
	v_add_f32_dpp v66, v66, v66 quad_perm:[2,3,0,1] row_mask:0xf bank_mask:0xf bound_ctrl:1
	v_pk_mul_f32 v[62:63], v[138:139], v[132:133] op_sel_hi:[0,1]
	v_add_f32_dpp v58, v58, v58 row_half_mirror row_mask:0xf bank_mask:0xf bound_ctrl:1
	v_add_f32_dpp v66, v66, v66 row_half_mirror row_mask:0xf bank_mask:0xf bound_ctrl:1
	v_pk_fma_f32 v[62:63], v[92:93], v[128:129], v[62:63]
	v_add_f32_dpp v58, v58, v58 row_mirror row_mask:0xf bank_mask:0xf bound_ctrl:1
	v_add_f32_dpp v66, v66, v66 row_mirror row_mask:0xf bank_mask:0xf bound_ctrl:1
	v_pk_fma_f32 v[90:91], v[134:135], v[58:59], v[60:61] op_sel_hi:[1,0,1] neg_lo:[1,0,0] neg_hi:[1,0,0]
	v_pk_fma_f32 v[92:93], v[136:137], v[58:59], v[62:63] op_sel_hi:[1,0,1] neg_lo:[1,0,0] neg_hi:[1,0,0]
	v_cndmask_b32_e64 v67, v67, v66, s[40:41]
	s_waitcnt lgkmcnt(6)
	ds_read_b128 v[100:103], v49 offset:7936
	ds_read_b32 v116, v50 offset:8192
	ds_read_b128 v[108:111], v49 offset:8704
	ds_read_b128 v[104:107], v49 offset:8448
	ds_read_b128 v[112:115], v49 offset:8960
	ds_read_b128 v[96:99], v49 offset:7680
	v_pk_mul_f32 v[56:57], v[90:91], v[144:145]
	v_pk_mul_f32 v[64:65], v[120:121], v[92:93]
	v_pk_fma_f32 v[56:57], v[92:93], v[146:147], v[56:57]
	v_pk_fma_f32 v[64:65], v[118:119], v[90:91], v[64:65]
	v_add_f32_e32 v58, v56, v57
	v_add_f32_e32 v66, v64, v65
	v_pk_mul_f32 v[60:61], v[160:161], v[152:153] op_sel_hi:[0,1]
	v_add_f32_dpp v58, v58, v58 quad_perm:[1,0,3,2] row_mask:0xf bank_mask:0xf bound_ctrl:1
	v_add_f32_dpp v66, v66, v66 quad_perm:[1,0,3,2] row_mask:0xf bank_mask:0xf bound_ctrl:1
	v_pk_fma_f32 v[60:61], v[90:91], v[148:149], v[60:61]
	v_add_f32_dpp v58, v58, v58 quad_perm:[2,3,0,1] row_mask:0xf bank_mask:0xf bound_ctrl:1
	v_add_f32_dpp v66, v66, v66 quad_perm:[2,3,0,1] row_mask:0xf bank_mask:0xf bound_ctrl:1
	v_pk_mul_f32 v[62:63], v[160:161], v[154:155] op_sel_hi:[0,1]
	v_add_f32_dpp v58, v58, v58 row_half_mirror row_mask:0xf bank_mask:0xf bound_ctrl:1
	v_add_f32_dpp v66, v66, v66 row_half_mirror row_mask:0xf bank_mask:0xf bound_ctrl:1
	v_pk_fma_f32 v[62:63], v[92:93], v[150:151], v[62:63]
	v_add_f32_dpp v58, v58, v58 row_mirror row_mask:0xf bank_mask:0xf bound_ctrl:1
	v_add_f32_dpp v66, v66, v66 row_mirror row_mask:0xf bank_mask:0xf bound_ctrl:1
	v_pk_fma_f32 v[90:91], v[156:157], v[58:59], v[60:61] op_sel_hi:[1,0,1] neg_lo:[1,0,0] neg_hi:[1,0,0]
	v_pk_fma_f32 v[92:93], v[158:159], v[58:59], v[62:63] op_sel_hi:[1,0,1] neg_lo:[1,0,0] neg_hi:[1,0,0]
	v_cndmask_b32_e64 v67, v67, v66, s[42:43]
	s_waitcnt lgkmcnt(6)
	ds_read_b128 v[122:125], v49 offset:9472
	ds_read_b32 v138, v50 offset:9728
	ds_read_b128 v[130:133], v49 offset:10240
	ds_read_b128 v[126:129], v49 offset:9984
	ds_read_b128 v[134:137], v49 offset:10496
	ds_read_b128 v[118:121], v49 offset:9216
	v_pk_mul_f32 v[56:57], v[90:91], v[72:73]
	v_pk_mul_f32 v[64:65], v[142:143], v[92:93]
	v_pk_fma_f32 v[56:57], v[92:93], v[74:75], v[56:57]
	v_pk_fma_f32 v[64:65], v[140:141], v[90:91], v[64:65]
	v_add_f32_e32 v58, v56, v57
	v_add_f32_e32 v66, v64, v65
	v_pk_mul_f32 v[60:61], v[88:89], v[80:81] op_sel_hi:[0,1]
	v_add_f32_dpp v58, v58, v58 quad_perm:[1,0,3,2] row_mask:0xf bank_mask:0xf bound_ctrl:1
	v_add_f32_dpp v66, v66, v66 quad_perm:[1,0,3,2] row_mask:0xf bank_mask:0xf bound_ctrl:1
	v_pk_fma_f32 v[60:61], v[90:91], v[76:77], v[60:61]
	v_add_f32_dpp v58, v58, v58 quad_perm:[2,3,0,1] row_mask:0xf bank_mask:0xf bound_ctrl:1
	v_add_f32_dpp v66, v66, v66 quad_perm:[2,3,0,1] row_mask:0xf bank_mask:0xf bound_ctrl:1
	v_pk_mul_f32 v[62:63], v[88:89], v[82:83] op_sel_hi:[0,1]
	v_add_f32_dpp v58, v58, v58 row_half_mirror row_mask:0xf bank_mask:0xf bound_ctrl:1
	v_add_f32_dpp v66, v66, v66 row_half_mirror row_mask:0xf bank_mask:0xf bound_ctrl:1
	v_pk_fma_f32 v[62:63], v[92:93], v[78:79], v[62:63]
	v_add_f32_dpp v58, v58, v58 row_mirror row_mask:0xf bank_mask:0xf bound_ctrl:1
	v_add_f32_dpp v66, v66, v66 row_mirror row_mask:0xf bank_mask:0xf bound_ctrl:1
	v_pk_fma_f32 v[90:91], v[84:85], v[58:59], v[60:61] op_sel_hi:[1,0,1] neg_lo:[1,0,0] neg_hi:[1,0,0]
	v_pk_fma_f32 v[92:93], v[86:87], v[58:59], v[62:63] op_sel_hi:[1,0,1] neg_lo:[1,0,0] neg_hi:[1,0,0]
	v_cndmask_b32_e64 v67, v67, v66, s[44:45]
	s_waitcnt lgkmcnt(6)
; DI void scan_item(const Params& p, int item, char* smem) {
;     ...
;   auto ldstep = [&](const float* b) {
;     StepIn x;
;     x.r = *(const f32x4v*)(b + cg4); x.k = *(const f32x4v*)(b + 64 + cg4); x.v = b[voff];
;     x.w = *(const f32x4v*)(b + 192 + cg4); x.d = *(const f32x4v*)(b + 256 + cg4); x.b = *(const f32x4v*)(b + 320 + cg4);
;     return x;
;   };
;   for (int ci = 0; ci < nch; ci++) {
;     if (ci + 1 < nch) gload(ci + 1);
;     const float* base = sIn + (ci & 1) * 16 * 6 * 64;
;     float ykeep = 0.f;
;     StepIn cur = ldstep(base);
; #pragma unroll
;     for (int st = 0; st < 16; st++) {
;       StepIn nxt = cur;
;       if (st + 1 < 16) nxt = ldstep(base + (st + 1) * 6 * 64);
;       __builtin_amdgcn_sched_barrier(0);
;       f32x2 ra = {cur.r.x, cur.r.y}, rb = {cur.r.z, cur.r.w}, ka = {cur.k.x, cur.k.y}, kb = {cur.k.z, cur.k.w};
;       f32x2 wa = {cur.w.x, cur.w.y}, wb = {cur.w.z, cur.w.w}, da = {cur.d.x, cur.d.y}, db = {cur.d.z, cur.d.w};
;       f32x2 ba = {cur.b.x, cur.b.y}, bb2 = {cur.b.z, cur.b.w};
;       f32x2 pp = Sa * ka + Sb * kb;
;       float sa = allreduce16(pp.x + pp.y);
;       f32x2 vv2 = {cur.v, cur.v};
;       f32x2 sa2 = {sa, sa};
;       Sa = (Sa * wa + vv2 * da) - sa2 * ba;
;       Sb = (Sb * wb + vv2 * db) - sa2 * bb2;
;       f32x2 yy = Sa * ra + Sb * rb;
;       float y = allreduce16(yy.x + yy.y);
;       ykeep = (l16 == st) ? y : ykeep;
;       cur = nxt;
;     }
	ds_read_b128 v[144:147], v49 offset:11008
	ds_read_b32 v160, v50 offset:11264
	ds_read_b128 v[152:155], v49 offset:11776
	ds_read_b128 v[148:151], v49 offset:11520
	ds_read_b128 v[156:159], v49 offset:12032
	ds_read_b128 v[140:143], v49 offset:10752
	v_pk_mul_f32 v[56:57], v[90:91], v[100:101]
	v_pk_mul_f32 v[64:65], v[70:71], v[92:93]
	v_pk_fma_f32 v[56:57], v[92:93], v[102:103], v[56:57]
	v_pk_fma_f32 v[64:65], v[68:69], v[90:91], v[64:65]
	v_add_f32_e32 v58, v56, v57
	v_add_f32_e32 v66, v64, v65
	v_pk_mul_f32 v[60:61], v[116:117], v[108:109] op_sel_hi:[0,1]
	v_add_f32_dpp v58, v58, v58 quad_perm:[1,0,3,2] row_mask:0xf bank_mask:0xf bound_ctrl:1
	v_add_f32_dpp v66, v66, v66 quad_perm:[1,0,3,2] row_mask:0xf bank_mask:0xf bound_ctrl:1
	v_pk_fma_f32 v[60:61], v[90:91], v[104:105], v[60:61]
	v_add_f32_dpp v58, v58, v58 quad_perm:[2,3,0,1] row_mask:0xf bank_mask:0xf bound_ctrl:1
	v_add_f32_dpp v66, v66, v66 quad_perm:[2,3,0,1] row_mask:0xf bank_mask:0xf bound_ctrl:1
	v_pk_mul_f32 v[62:63], v[116:117], v[110:111] op_sel_hi:[0,1]
	v_add_f32_dpp v58, v58, v58 row_half_mirror row_mask:0xf bank_mask:0xf bound_ctrl:1
	v_add_f32_dpp v66, v66, v66 row_half_mirror row_mask:0xf bank_mask:0xf bound_ctrl:1
	v_pk_fma_f32 v[62:63], v[92:93], v[106:107], v[62:63]
	v_add_f32_dpp v58, v58, v58 row_mirror row_mask:0xf bank_mask:0xf bound_ctrl:1
	v_add_f32_dpp v66, v66, v66 row_mirror row_mask:0xf bank_mask:0xf bound_ctrl:1
	v_pk_fma_f32 v[90:91], v[112:113], v[58:59], v[60:61] op_sel_hi:[1,0,1] neg_lo:[1,0,0] neg_hi:[1,0,0]
	v_pk_fma_f32 v[92:93], v[114:115], v[58:59], v[62:63] op_sel_hi:[1,0,1] neg_lo:[1,0,0] neg_hi:[1,0,0]
	v_cndmask_b32_e64 v67, v67, v66, s[46:47]
	s_waitcnt lgkmcnt(6)
	ds_read_b128 v[72:75], v49 offset:12544
	ds_read_b32 v88, v50 offset:12800
	ds_read_b128 v[80:83], v49 offset:13312
	ds_read_b128 v[76:79], v49 offset:13056
	ds_read_b128 v[84:87], v49 offset:13568
	ds_read_b128 v[68:71], v49 offset:12288
	v_pk_mul_f32 v[56:57], v[90:91], v[122:123]
	v_pk_mul_f32 v[64:65], v[98:99], v[92:93]
	v_pk_fma_f32 v[56:57], v[92:93], v[124:125], v[56:57]
	v_pk_fma_f32 v[64:65], v[96:97], v[90:91], v[64:65]
	v_add_f32_e32 v58, v56, v57
	v_add_f32_e32 v66, v64, v65
	v_pk_mul_f32 v[60:61], v[138:139], v[130:131] op_sel_hi:[0,1]
	v_add_f32_dpp v58, v58, v58 quad_perm:[1,0,3,2] row_mask:0xf bank_mask:0xf bound_ctrl:1
	v_add_f32_dpp v66, v66, v66 quad_perm:[1,0,3,2] row_mask:0xf bank_mask:0xf bound_ctrl:1
	v_pk_fma_f32 v[60:61], v[90:91], v[126:127], v[60:61]
	v_add_f32_dpp v58, v58, v58 quad_perm:[2,3,0,1] row_mask:0xf bank_mask:0xf bound_ctrl:1
	v_add_f32_dpp v66, v66, v66 quad_perm:[2,3,0,1] row_mask:0xf bank_mask:0xf bound_ctrl:1
	v_pk_mul_f32 v[62:63], v[138:139], v[132:133] op_sel_hi:[0,1]
	v_add_f32_dpp v58, v58, v58 row_half_mirror row_mask:0xf bank_mask:0xf bound_ctrl:1
	v_add_f32_dpp v66, v66, v66 row_half_mirror row_mask:0xf bank_mask:0xf bound_ctrl:1
	v_pk_fma_f32 v[62:63], v[92:93], v[128:129], v[62:63]
	v_add_f32_dpp v58, v58, v58 row_mirror row_mask:0xf bank_mask:0xf bound_ctrl:1
	v_add_f32_dpp v66, v66, v66 row_mirror row_mask:0xf bank_mask:0xf bound_ctrl:1
	v_pk_fma_f32 v[90:91], v[134:135], v[58:59], v[60:61] op_sel_hi:[1,0,1] neg_lo:[1,0,0] neg_hi:[1,0,0]
	v_pk_fma_f32 v[92:93], v[136:137], v[58:59], v[62:63] op_sel_hi:[1,0,1] neg_lo:[1,0,0] neg_hi:[1,0,0]
	v_cndmask_b32_e64 v67, v67, v66, s[48:49]
	s_waitcnt lgkmcnt(6)
	ds_read_b128 v[100:103], v49 offset:14080
	ds_read_b32 v116, v50 offset:14336
	ds_read_b128 v[108:111], v49 offset:14848
	ds_read_b128 v[104:107], v49 offset:14592
	ds_read_b128 v[112:115], v49 offset:15104
	ds_read_b128 v[96:99], v49 offset:13824
	v_pk_mul_f32 v[56:57], v[90:91], v[144:145]
	v_pk_mul_f32 v[64:65], v[120:121], v[92:93]
	v_pk_fma_f32 v[56:57], v[92:93], v[146:147], v[56:57]
	v_pk_fma_f32 v[64:65], v[118:119], v[90:91], v[64:65]
	v_add_f32_e32 v58, v56, v57
	v_add_f32_e32 v66, v64, v65
	v_pk_mul_f32 v[60:61], v[160:161], v[152:153] op_sel_hi:[0,1]
	v_add_f32_dpp v58, v58, v58 quad_perm:[1,0,3,2] row_mask:0xf bank_mask:0xf bound_ctrl:1
	v_add_f32_dpp v66, v66, v66 quad_perm:[1,0,3,2] row_mask:0xf bank_mask:0xf bound_ctrl:1
	v_pk_fma_f32 v[60:61], v[90:91], v[148:149], v[60:61]
	v_add_f32_dpp v58, v58, v58 quad_perm:[2,3,0,1] row_mask:0xf bank_mask:0xf bound_ctrl:1
	v_add_f32_dpp v66, v66, v66 quad_perm:[2,3,0,1] row_mask:0xf bank_mask:0xf bound_ctrl:1
	v_pk_mul_f32 v[62:63], v[160:161], v[154:155] op_sel_hi:[0,1]
	v_add_f32_dpp v58, v58, v58 row_half_mirror row_mask:0xf bank_mask:0xf bound_ctrl:1
	v_add_f32_dpp v66, v66, v66 row_half_mirror row_mask:0xf bank_mask:0xf bound_ctrl:1
	v_pk_fma_f32 v[62:63], v[92:93], v[150:151], v[62:63]
	v_add_f32_dpp v58, v58, v58 row_mirror row_mask:0xf bank_mask:0xf bound_ctrl:1
	v_add_f32_dpp v66, v66, v66 row_mirror row_mask:0xf bank_mask:0xf bound_ctrl:1
	v_pk_fma_f32 v[90:91], v[156:157], v[58:59], v[60:61] op_sel_hi:[1,0,1] neg_lo:[1,0,0] neg_hi:[1,0,0]
	v_pk_fma_f32 v[92:93], v[158:159], v[58:59], v[62:63] op_sel_hi:[1,0,1] neg_lo:[1,0,0] neg_hi:[1,0,0]
	v_cndmask_b32_e64 v67, v67, v66, s[50:51]
	s_waitcnt lgkmcnt(6)
; DI void scan_item(const Params& p, int item, char* smem) {
;     ...
;   auto ldstep = [&](const float* b) {
;     StepIn x;
;     x.r = *(const f32x4v*)(b + cg4); x.k = *(const f32x4v*)(b + 64 + cg4); x.v = b[voff];
;     x.w = *(const f32x4v*)(b + 192 + cg4); x.d = *(const f32x4v*)(b + 256 + cg4); x.b = *(const f32x4v*)(b + 320 + cg4);
;     return x;
;   };
;   for (int ci = 0; ci < nch; ci++) {
;     if (ci + 1 < nch) gload(ci + 1);
;     const float* base = sIn + (ci & 1) * 16 * 6 * 64;
;     float ykeep = 0.f;
;     StepIn cur = ldstep(base);
; #pragma unroll
;     for (int st = 0; st < 16; st++) {
;       StepIn nxt = cur;
;       if (st + 1 < 16) nxt = ldstep(base + (st + 1) * 6 * 64);
;       __builtin_amdgcn_sched_barrier(0);
;       f32x2 ra = {cur.r.x, cur.r.y}, rb = {cur.r.z, cur.r.w}, ka = {cur.k.x, cur.k.y}, kb = {cur.k.z, cur.k.w};
;       f32x2 wa = {cur.w.x, cur.w.y}, wb = {cur.w.z, cur.w.w}, da = {cur.d.x, cur.d.y}, db = {cur.d.z, cur.d.w};
;       f32x2 ba = {cur.b.x, cur.b.y}, bb2 = {cur.b.z, cur.b.w};
;       f32x2 pp = Sa * ka + Sb * kb;
;       float sa = allreduce16(pp.x + pp.y);
;       f32x2 vv2 = {cur.v, cur.v};
;       f32x2 sa2 = {sa, sa};
;       Sa = (Sa * wa + vv2 * da) - sa2 * ba;
;       Sb = (Sb * wb + vv2 * db) - sa2 * bb2;
;       f32x2 yy = Sa * ra + Sb * rb;
;       float y = allreduce16(yy.x + yy.y);
;       ykeep = (l16 == st) ? y : ykeep;
;       cur = nxt;
;     }
	ds_read_b128 v[122:125], v49 offset:15616
	ds_read_b32 v138, v50 offset:15872
	ds_read_b128 v[130:133], v49 offset:16384
	ds_read_b128 v[126:129], v49 offset:16128
	ds_read_b128 v[134:137], v49 offset:16640
	ds_read_b128 v[118:121], v49 offset:15360
	v_pk_mul_f32 v[56:57], v[90:91], v[72:73]
	v_pk_mul_f32 v[64:65], v[142:143], v[92:93]
	v_pk_fma_f32 v[56:57], v[92:93], v[74:75], v[56:57]
	v_pk_fma_f32 v[64:65], v[140:141], v[90:91], v[64:65]
	v_add_f32_e32 v58, v56, v57
	v_add_f32_e32 v66, v64, v65
	v_pk_mul_f32 v[60:61], v[88:89], v[80:81] op_sel_hi:[0,1]
	v_add_f32_dpp v58, v58, v58 quad_perm:[1,0,3,2] row_mask:0xf bank_mask:0xf bound_ctrl:1
	v_add_f32_dpp v66, v66, v66 quad_perm:[1,0,3,2] row_mask:0xf bank_mask:0xf bound_ctrl:1
	v_pk_fma_f32 v[60:61], v[90:91], v[76:77], v[60:61]
	v_add_f32_dpp v58, v58, v58 quad_perm:[2,3,0,1] row_mask:0xf bank_mask:0xf bound_ctrl:1
	v_add_f32_dpp v66, v66, v66 quad_perm:[2,3,0,1] row_mask:0xf bank_mask:0xf bound_ctrl:1
	v_pk_mul_f32 v[62:63], v[88:89], v[82:83] op_sel_hi:[0,1]
	v_add_f32_dpp v58, v58, v58 row_half_mirror row_mask:0xf bank_mask:0xf bound_ctrl:1
	v_add_f32_dpp v66, v66, v66 row_half_mirror row_mask:0xf bank_mask:0xf bound_ctrl:1
	v_pk_fma_f32 v[62:63], v[92:93], v[78:79], v[62:63]
	v_add_f32_dpp v58, v58, v58 row_mirror row_mask:0xf bank_mask:0xf bound_ctrl:1
	v_add_f32_dpp v66, v66, v66 row_mirror row_mask:0xf bank_mask:0xf bound_ctrl:1
	v_pk_fma_f32 v[90:91], v[84:85], v[58:59], v[60:61] op_sel_hi:[1,0,1] neg_lo:[1,0,0] neg_hi:[1,0,0]
	v_pk_fma_f32 v[92:93], v[86:87], v[58:59], v[62:63] op_sel_hi:[1,0,1] neg_lo:[1,0,0] neg_hi:[1,0,0]
	v_cndmask_b32_e64 v67, v67, v66, s[52:53]
	s_waitcnt lgkmcnt(6)
	ds_read_b128 v[144:147], v49 offset:17152
	ds_read_b32 v160, v50 offset:17408
	ds_read_b128 v[152:155], v49 offset:17920
	ds_read_b128 v[148:151], v49 offset:17664
	ds_read_b128 v[156:159], v49 offset:18176
	ds_read_b128 v[140:143], v49 offset:16896
	v_pk_mul_f32 v[56:57], v[90:91], v[100:101]
	v_pk_mul_f32 v[64:65], v[70:71], v[92:93]
	v_pk_fma_f32 v[56:57], v[92:93], v[102:103], v[56:57]
	v_pk_fma_f32 v[64:65], v[68:69], v[90:91], v[64:65]
	v_add_f32_e32 v58, v56, v57
	v_add_f32_e32 v66, v64, v65
	v_pk_mul_f32 v[60:61], v[116:117], v[108:109] op_sel_hi:[0,1]
	v_add_f32_dpp v58, v58, v58 quad_perm:[1,0,3,2] row_mask:0xf bank_mask:0xf bound_ctrl:1
	v_add_f32_dpp v66, v66, v66 quad_perm:[1,0,3,2] row_mask:0xf bank_mask:0xf bound_ctrl:1
	v_pk_fma_f32 v[60:61], v[90:91], v[104:105], v[60:61]
	v_add_f32_dpp v58, v58, v58 quad_perm:[2,3,0,1] row_mask:0xf bank_mask:0xf bound_ctrl:1
	v_add_f32_dpp v66, v66, v66 quad_perm:[2,3,0,1] row_mask:0xf bank_mask:0xf bound_ctrl:1
	v_pk_mul_f32 v[62:63], v[116:117], v[110:111] op_sel_hi:[0,1]
	v_add_f32_dpp v58, v58, v58 row_half_mirror row_mask:0xf bank_mask:0xf bound_ctrl:1
	v_add_f32_dpp v66, v66, v66 row_half_mirror row_mask:0xf bank_mask:0xf bound_ctrl:1
	v_pk_fma_f32 v[62:63], v[92:93], v[106:107], v[62:63]
	v_add_f32_dpp v58, v58, v58 row_mirror row_mask:0xf bank_mask:0xf bound_ctrl:1
	v_add_f32_dpp v66, v66, v66 row_mirror row_mask:0xf bank_mask:0xf bound_ctrl:1
	v_pk_fma_f32 v[90:91], v[112:113], v[58:59], v[60:61] op_sel_hi:[1,0,1] neg_lo:[1,0,0] neg_hi:[1,0,0]
	v_pk_fma_f32 v[92:93], v[114:115], v[58:59], v[62:63] op_sel_hi:[1,0,1] neg_lo:[1,0,0] neg_hi:[1,0,0]
	v_cndmask_b32_e64 v67, v67, v66, s[54:55]
	s_waitcnt lgkmcnt(6)
	ds_read_b128 v[72:75], v49 offset:18688
	ds_read_b32 v88, v50 offset:18944
	ds_read_b128 v[80:83], v49 offset:19456
	ds_read_b128 v[76:79], v49 offset:19200
	ds_read_b128 v[84:87], v49 offset:19712
	ds_read_b128 v[68:71], v49 offset:18432
	v_pk_mul_f32 v[56:57], v[90:91], v[122:123]
	v_pk_mul_f32 v[64:65], v[98:99], v[92:93]
	v_pk_fma_f32 v[56:57], v[92:93], v[124:125], v[56:57]
	v_pk_fma_f32 v[64:65], v[96:97], v[90:91], v[64:65]
	v_add_f32_e32 v58, v56, v57
	v_add_f32_e32 v66, v64, v65
	v_pk_mul_f32 v[60:61], v[138:139], v[130:131] op_sel_hi:[0,1]
	v_add_f32_dpp v58, v58, v58 quad_perm:[1,0,3,2] row_mask:0xf bank_mask:0xf bound_ctrl:1
	v_add_f32_dpp v66, v66, v66 quad_perm:[1,0,3,2] row_mask:0xf bank_mask:0xf bound_ctrl:1
	v_pk_fma_f32 v[60:61], v[90:91], v[126:127], v[60:61]
	v_add_f32_dpp v58, v58, v58 quad_perm:[2,3,0,1] row_mask:0xf bank_mask:0xf bound_ctrl:1
	v_add_f32_dpp v66, v66, v66 quad_perm:[2,3,0,1] row_mask:0xf bank_mask:0xf bound_ctrl:1
	v_pk_mul_f32 v[62:63], v[138:139], v[132:133] op_sel_hi:[0,1]
	v_add_f32_dpp v58, v58, v58 row_half_mirror row_mask:0xf bank_mask:0xf bound_ctrl:1
	v_add_f32_dpp v66, v66, v66 row_half_mirror row_mask:0xf bank_mask:0xf bound_ctrl:1
	v_pk_fma_f32 v[62:63], v[92:93], v[128:129], v[62:63]
	v_add_f32_dpp v58, v58, v58 row_mirror row_mask:0xf bank_mask:0xf bound_ctrl:1
	v_add_f32_dpp v66, v66, v66 row_mirror row_mask:0xf bank_mask:0xf bound_ctrl:1
	v_pk_fma_f32 v[90:91], v[134:135], v[58:59], v[60:61] op_sel_hi:[1,0,1] neg_lo:[1,0,0] neg_hi:[1,0,0]
	v_pk_fma_f32 v[92:93], v[136:137], v[58:59], v[62:63] op_sel_hi:[1,0,1] neg_lo:[1,0,0] neg_hi:[1,0,0]
	v_cndmask_b32_e64 v67, v67, v66, s[56:57]
	s_waitcnt lgkmcnt(6)
; DI void scan_item(const Params& p, int item, char* smem) {
;     ...
;   auto ldstep = [&](const float* b) {
;     StepIn x;
;     x.r = *(const f32x4v*)(b + cg4); x.k = *(const f32x4v*)(b + 64 + cg4); x.v = b[voff];
;     x.w = *(const f32x4v*)(b + 192 + cg4); x.d = *(const f32x4v*)(b + 256 + cg4); x.b = *(const f32x4v*)(b + 320 + cg4);
;     return x;
;   };
;   for (int ci = 0; ci < nch; ci++) {
;     if (ci + 1 < nch) gload(ci + 1);
;     const float* base = sIn + (ci & 1) * 16 * 6 * 64;
;     float ykeep = 0.f;
;     StepIn cur = ldstep(base);
; #pragma unroll
;     for (int st = 0; st < 16; st++) {
;       StepIn nxt = cur;
;       if (st + 1 < 16) nxt = ldstep(base + (st + 1) * 6 * 64);
;       __builtin_amdgcn_sched_barrier(0);
;       f32x2 ra = {cur.r.x, cur.r.y}, rb = {cur.r.z, cur.r.w}, ka = {cur.k.x, cur.k.y}, kb = {cur.k.z, cur.k.w};
;       f32x2 wa = {cur.w.x, cur.w.y}, wb = {cur.w.z, cur.w.w}, da = {cur.d.x, cur.d.y}, db = {cur.d.z, cur.d.w};
;       f32x2 ba = {cur.b.x, cur.b.y}, bb2 = {cur.b.z, cur.b.w};
;       f32x2 pp = Sa * ka + Sb * kb;
;       float sa = allreduce16(pp.x + pp.y);
;       f32x2 vv2 = {cur.v, cur.v};
;       f32x2 sa2 = {sa, sa};
;       Sa = (Sa * wa + vv2 * da) - sa2 * ba;
;       Sb = (Sb * wb + vv2 * db) - sa2 * bb2;
;       f32x2 yy = Sa * ra + Sb * rb;
;       float y = allreduce16(yy.x + yy.y);
;       ykeep = (l16 == st) ? y : ykeep;
;       cur = nxt;
;     }
	ds_read_b128 v[100:103], v49 offset:20224
	ds_read_b32 v116, v50 offset:20480
	ds_read_b128 v[108:111], v49 offset:20992
	ds_read_b128 v[104:107], v49 offset:20736
	ds_read_b128 v[112:115], v49 offset:21248
	ds_read_b128 v[96:99], v49 offset:19968
	v_pk_mul_f32 v[56:57], v[90:91], v[144:145]
	v_pk_mul_f32 v[64:65], v[120:121], v[92:93]
	v_pk_fma_f32 v[56:57], v[92:93], v[146:147], v[56:57]
	v_pk_fma_f32 v[64:65], v[118:119], v[90:91], v[64:65]
	v_add_f32_e32 v58, v56, v57
	v_add_f32_e32 v66, v64, v65
	v_pk_mul_f32 v[60:61], v[160:161], v[152:153] op_sel_hi:[0,1]
	v_add_f32_dpp v58, v58, v58 quad_perm:[1,0,3,2] row_mask:0xf bank_mask:0xf bound_ctrl:1
	v_add_f32_dpp v66, v66, v66 quad_perm:[1,0,3,2] row_mask:0xf bank_mask:0xf bound_ctrl:1
	v_pk_fma_f32 v[60:61], v[90:91], v[148:149], v[60:61]
	v_add_f32_dpp v58, v58, v58 quad_perm:[2,3,0,1] row_mask:0xf bank_mask:0xf bound_ctrl:1
	v_add_f32_dpp v66, v66, v66 quad_perm:[2,3,0,1] row_mask:0xf bank_mask:0xf bound_ctrl:1
	v_pk_mul_f32 v[62:63], v[160:161], v[154:155] op_sel_hi:[0,1]
	v_add_f32_dpp v58, v58, v58 row_half_mirror row_mask:0xf bank_mask:0xf bound_ctrl:1
	v_add_f32_dpp v66, v66, v66 row_half_mirror row_mask:0xf bank_mask:0xf bound_ctrl:1
	v_pk_fma_f32 v[62:63], v[92:93], v[150:151], v[62:63]
	v_add_f32_dpp v58, v58, v58 row_mirror row_mask:0xf bank_mask:0xf bound_ctrl:1
	v_add_f32_dpp v66, v66, v66 row_mirror row_mask:0xf bank_mask:0xf bound_ctrl:1
	v_pk_fma_f32 v[90:91], v[156:157], v[58:59], v[60:61] op_sel_hi:[1,0,1] neg_lo:[1,0,0] neg_hi:[1,0,0]
	v_pk_fma_f32 v[92:93], v[158:159], v[58:59], v[62:63] op_sel_hi:[1,0,1] neg_lo:[1,0,0] neg_hi:[1,0,0]
	v_cndmask_b32_e64 v67, v67, v66, s[58:59]
	s_waitcnt lgkmcnt(6)
	ds_read_b128 v[122:125], v49 offset:21760
	ds_read_b32 v138, v50 offset:22016
	ds_read_b128 v[130:133], v49 offset:22528
	ds_read_b128 v[126:129], v49 offset:22272
	ds_read_b128 v[134:137], v49 offset:22784
	ds_read_b128 v[118:121], v49 offset:21504
	v_pk_mul_f32 v[56:57], v[90:91], v[72:73]
	v_pk_mul_f32 v[64:65], v[142:143], v[92:93]
	v_pk_fma_f32 v[56:57], v[92:93], v[74:75], v[56:57]
	v_pk_fma_f32 v[64:65], v[140:141], v[90:91], v[64:65]
	v_add_f32_e32 v58, v56, v57
	v_add_f32_e32 v66, v64, v65
	v_pk_mul_f32 v[60:61], v[88:89], v[80:81] op_sel_hi:[0,1]
	v_add_f32_dpp v58, v58, v58 quad_perm:[1,0,3,2] row_mask:0xf bank_mask:0xf bound_ctrl:1
	v_add_f32_dpp v66, v66, v66 quad_perm:[1,0,3,2] row_mask:0xf bank_mask:0xf bound_ctrl:1
	v_pk_fma_f32 v[60:61], v[90:91], v[76:77], v[60:61]
	v_add_f32_dpp v58, v58, v58 quad_perm:[2,3,0,1] row_mask:0xf bank_mask:0xf bound_ctrl:1
	v_add_f32_dpp v66, v66, v66 quad_perm:[2,3,0,1] row_mask:0xf bank_mask:0xf bound_ctrl:1
	v_pk_mul_f32 v[62:63], v[88:89], v[82:83] op_sel_hi:[0,1]
	v_add_f32_dpp v58, v58, v58 row_half_mirror row_mask:0xf bank_mask:0xf bound_ctrl:1
	v_add_f32_dpp v66, v66, v66 row_half_mirror row_mask:0xf bank_mask:0xf bound_ctrl:1
	v_pk_fma_f32 v[62:63], v[92:93], v[78:79], v[62:63]
	v_add_f32_dpp v58, v58, v58 row_mirror row_mask:0xf bank_mask:0xf bound_ctrl:1
	v_add_f32_dpp v66, v66, v66 row_mirror row_mask:0xf bank_mask:0xf bound_ctrl:1
	v_pk_fma_f32 v[90:91], v[84:85], v[58:59], v[60:61] op_sel_hi:[1,0,1] neg_lo:[1,0,0] neg_hi:[1,0,0]
	v_pk_fma_f32 v[92:93], v[86:87], v[58:59], v[62:63] op_sel_hi:[1,0,1] neg_lo:[1,0,0] neg_hi:[1,0,0]
	v_cndmask_b32_e64 v67, v67, v66, s[60:61]
	s_waitcnt lgkmcnt(6)
	ds_read_b128 v[144:147], v49 offset:23296
	ds_read_b32 v160, v50 offset:23552
	ds_read_b128 v[152:155], v49 offset:24064
	ds_read_b128 v[148:151], v49 offset:23808
	ds_read_b128 v[156:159], v49 offset:24320
	ds_read_b128 v[140:143], v49 offset:23040
	v_pk_mul_f32 v[56:57], v[90:91], v[100:101]
	v_pk_mul_f32 v[64:65], v[70:71], v[92:93]
	v_pk_fma_f32 v[56:57], v[92:93], v[102:103], v[56:57]
	v_pk_fma_f32 v[64:65], v[68:69], v[90:91], v[64:65]
	v_add_f32_e32 v58, v56, v57
	v_add_f32_e32 v66, v64, v65
	v_pk_mul_f32 v[60:61], v[116:117], v[108:109] op_sel_hi:[0,1]
	v_add_f32_dpp v58, v58, v58 quad_perm:[1,0,3,2] row_mask:0xf bank_mask:0xf bound_ctrl:1
	v_add_f32_dpp v66, v66, v66 quad_perm:[1,0,3,2] row_mask:0xf bank_mask:0xf bound_ctrl:1
	v_pk_fma_f32 v[60:61], v[90:91], v[104:105], v[60:61]
	v_add_f32_dpp v58, v58, v58 quad_perm:[2,3,0,1] row_mask:0xf bank_mask:0xf bound_ctrl:1
	v_add_f32_dpp v66, v66, v66 quad_perm:[2,3,0,1] row_mask:0xf bank_mask:0xf bound_ctrl:1
	v_pk_mul_f32 v[62:63], v[116:117], v[110:111] op_sel_hi:[0,1]
	v_add_f32_dpp v58, v58, v58 row_half_mirror row_mask:0xf bank_mask:0xf bound_ctrl:1
	v_add_f32_dpp v66, v66, v66 row_half_mirror row_mask:0xf bank_mask:0xf bound_ctrl:1
	v_pk_fma_f32 v[62:63], v[92:93], v[106:107], v[62:63]
	v_add_f32_dpp v58, v58, v58 row_mirror row_mask:0xf bank_mask:0xf bound_ctrl:1
	v_add_f32_dpp v66, v66, v66 row_mirror row_mask:0xf bank_mask:0xf bound_ctrl:1
	v_pk_fma_f32 v[90:91], v[112:113], v[58:59], v[60:61] op_sel_hi:[1,0,1] neg_lo:[1,0,0] neg_hi:[1,0,0]
	v_pk_fma_f32 v[92:93], v[114:115], v[58:59], v[62:63] op_sel_hi:[1,0,1] neg_lo:[1,0,0] neg_hi:[1,0,0]
	v_cndmask_b32_e64 v67, v67, v66, s[62:63]
	s_waitcnt lgkmcnt(6)
; DI void scan_item(const Params& p, int item, char* smem) {
;     ...
;   auto lstore = [&](int buf) {
; #pragma unroll
;     for (int i = 0; i < 3; i++) {
;       int id = tid + i * 256;
;       int st = id / 48, rem = id % 48, vec = rem >> 3, part = rem & 7;
;       h8 hv = __builtin_bit_cast(h8, rg_[i]);
;       f8 fv = __builtin_convertvector(hv, f8);
;       float* d = sIn + ((buf * 16 + st) * 6 + vec) * 64 + part * 8;
;       *(f32x4v*)d = f32x4v{fv[0], fv[1], fv[2], fv[3]};
;       *(f32x4v*)(d + 4) = f32x4v{fv[4], fv[5], fv[6], fv[7]};
;     }
;   };
;     ...
;     for (int st = 0; st < 16; st++) {
;       StepIn nxt = cur;
;       if (st + 1 < 16) nxt = ldstep(base + (st + 1) * 6 * 64);
;       __builtin_amdgcn_sched_barrier(0);
;       f32x2 ra = {cur.r.x, cur.r.y}, rb = {cur.r.z, cur.r.w}, ka = {cur.k.x, cur.k.y}, kb = {cur.k.z, cur.k.w};
;       f32x2 wa = {cur.w.x, cur.w.y}, wb = {cur.w.z, cur.w.w}, da = {cur.d.x, cur.d.y}, db = {cur.d.z, cur.d.w};
;       f32x2 ba = {cur.b.x, cur.b.y}, bb2 = {cur.b.z, cur.b.w};
;       f32x2 pp = Sa * ka + Sb * kb;
;       float sa = allreduce16(pp.x + pp.y);
;       f32x2 vv2 = {cur.v, cur.v};
;       f32x2 sa2 = {sa, sa};
;       Sa = (Sa * wa + vv2 * da) - sa2 * ba;
;       Sb = (Sb * wb + vv2 * db) - sa2 * bb2;
;       f32x2 yy = Sa * ra + Sb * rb;
;       float y = allreduce16(yy.x + yy.y);
;       ykeep = (l16 == st) ? y : ykeep;
;       cur = nxt;
;     }
;     { _Float16 yh = (_Float16)ykeep; yb[(long)tof(ci * 16 + l16) * 256 + rowl] = __builtin_bit_cast(u16, yh); }
;     if (ci + 1 < nch) lstore((ci + 1) & 1);
;     __syncthreads();
;   }
	v_pk_mul_f32 v[56:57], v[90:91], v[122:123]
	v_pk_mul_f32 v[64:65], v[98:99], v[92:93]
	v_pk_fma_f32 v[56:57], v[92:93], v[124:125], v[56:57]
	v_pk_fma_f32 v[64:65], v[96:97], v[90:91], v[64:65]
	v_add_f32_e32 v58, v56, v57
	v_add_f32_e32 v66, v64, v65
	v_pk_mul_f32 v[60:61], v[138:139], v[130:131] op_sel_hi:[0,1]
	v_add_f32_dpp v58, v58, v58 quad_perm:[1,0,3,2] row_mask:0xf bank_mask:0xf bound_ctrl:1
	v_add_f32_dpp v66, v66, v66 quad_perm:[1,0,3,2] row_mask:0xf bank_mask:0xf bound_ctrl:1
	v_pk_fma_f32 v[60:61], v[90:91], v[126:127], v[60:61]
	v_add_f32_dpp v58, v58, v58 quad_perm:[2,3,0,1] row_mask:0xf bank_mask:0xf bound_ctrl:1
	v_add_f32_dpp v66, v66, v66 quad_perm:[2,3,0,1] row_mask:0xf bank_mask:0xf bound_ctrl:1
	v_pk_mul_f32 v[62:63], v[138:139], v[132:133] op_sel_hi:[0,1]
	v_add_f32_dpp v58, v58, v58 row_half_mirror row_mask:0xf bank_mask:0xf bound_ctrl:1
	v_add_f32_dpp v66, v66, v66 row_half_mirror row_mask:0xf bank_mask:0xf bound_ctrl:1
	v_pk_fma_f32 v[62:63], v[92:93], v[128:129], v[62:63]
	v_add_f32_dpp v58, v58, v58 row_mirror row_mask:0xf bank_mask:0xf bound_ctrl:1
	v_add_f32_dpp v66, v66, v66 row_mirror row_mask:0xf bank_mask:0xf bound_ctrl:1
	v_pk_fma_f32 v[90:91], v[134:135], v[58:59], v[60:61] op_sel_hi:[1,0,1] neg_lo:[1,0,0] neg_hi:[1,0,0]
	v_pk_fma_f32 v[92:93], v[136:137], v[58:59], v[62:63] op_sel_hi:[1,0,1] neg_lo:[1,0,0] neg_hi:[1,0,0]
	v_cndmask_b32_e64 v67, v67, v66, s[64:65]
	s_waitcnt lgkmcnt(0)
	v_pk_mul_f32 v[56:57], v[90:91], v[144:145]
	v_pk_mul_f32 v[64:65], v[120:121], v[92:93]
	v_pk_fma_f32 v[56:57], v[92:93], v[146:147], v[56:57]
	v_pk_fma_f32 v[64:65], v[118:119], v[90:91], v[64:65]
	v_add_f32_e32 v58, v56, v57
	v_add_f32_e32 v66, v64, v65
	v_pk_mul_f32 v[60:61], v[160:161], v[152:153] op_sel_hi:[0,1]
	v_add_f32_dpp v58, v58, v58 quad_perm:[1,0,3,2] row_mask:0xf bank_mask:0xf bound_ctrl:1
	v_add_f32_dpp v66, v66, v66 quad_perm:[1,0,3,2] row_mask:0xf bank_mask:0xf bound_ctrl:1
	v_pk_fma_f32 v[60:61], v[90:91], v[148:149], v[60:61]
	v_add_f32_dpp v58, v58, v58 quad_perm:[2,3,0,1] row_mask:0xf bank_mask:0xf bound_ctrl:1
	v_add_f32_dpp v66, v66, v66 quad_perm:[2,3,0,1] row_mask:0xf bank_mask:0xf bound_ctrl:1
	v_pk_mul_f32 v[62:63], v[160:161], v[154:155] op_sel_hi:[0,1]
	v_add_f32_dpp v58, v58, v58 row_half_mirror row_mask:0xf bank_mask:0xf bound_ctrl:1
	v_add_f32_dpp v66, v66, v66 row_half_mirror row_mask:0xf bank_mask:0xf bound_ctrl:1
	v_pk_fma_f32 v[62:63], v[92:93], v[150:151], v[62:63]
	v_add_f32_dpp v58, v58, v58 row_mirror row_mask:0xf bank_mask:0xf bound_ctrl:1
	v_add_f32_dpp v66, v66, v66 row_mirror row_mask:0xf bank_mask:0xf bound_ctrl:1
	v_pk_fma_f32 v[90:91], v[156:157], v[58:59], v[60:61] op_sel_hi:[1,0,1] neg_lo:[1,0,0] neg_hi:[1,0,0]
	v_pk_fma_f32 v[92:93], v[158:159], v[58:59], v[62:63] op_sel_hi:[1,0,1] neg_lo:[1,0,0] neg_hi:[1,0,0]
	v_cndmask_b32_e64 v67, v67, v66, s[66:67]
	s_nop 0
	v_pk_mul_f32 v[64:65], v[142:143], v[92:93]
	v_pk_fma_f32 v[64:65], v[140:141], v[90:91], v[64:65]
	s_nop 0
	v_add_f32_e32 v66, v64, v65
	s_nop 0
	s_nop 0
	v_add_f32_dpp v66, v66, v66 quad_perm:[1,0,3,2] row_mask:0xf bank_mask:0xf bound_ctrl:1
	s_nop 0
	s_nop 0
	v_add_f32_dpp v66, v66, v66 quad_perm:[2,3,0,1] row_mask:0xf bank_mask:0xf bound_ctrl:1
	s_nop 0
	s_nop 0
	v_add_f32_dpp v66, v66, v66 row_half_mirror row_mask:0xf bank_mask:0xf bound_ctrl:1
	s_nop 1
	v_add_f32_dpp v66, v66, v66 row_mirror row_mask:0xf bank_mask:0xf bound_ctrl:1
	v_cndmask_b32_e64 v67, v67, v66, s[68:69]
	v_cvt_f16_f32_e32 v45, v67
	global_store_short v[242:243], v45, off
	s_add_i32 s12, s26, 16
	s_mov_b32 vcc_hi, 0x21e000
	s_cmp_eq_u32 s12, 0x100
	s_cselect_b32 vcc_lo, vcc_hi, 0xffffe000
	s_cmp_lg_u32 s36, 0
	s_cselect_b32 vcc_lo, 0x2000, vcc_lo
	s_ashr_i32 vcc_hi, vcc_lo, 31
	v_lshl_add_u64 v[242:243], v[242:243], 0, vcc
	s_waitcnt vmcnt(6)
	v_cvt_f32_f16_e32 v40, v0
	v_cvt_f32_f16_sdwa v41, v0 dst_sel:DWORD dst_unused:UNUSED_PAD src0_sel:WORD_1
	v_cvt_f32_f16_e32 v42, v1
	v_cvt_f32_f16_sdwa v43, v1 dst_sel:DWORD dst_unused:UNUSED_PAD src0_sel:WORD_1
	v_cvt_f32_f16_e32 v44, v2
	v_cvt_f32_f16_sdwa v45, v2 dst_sel:DWORD dst_unused:UNUSED_PAD src0_sel:WORD_1
	v_cvt_f32_f16_e32 v46, v3
	v_cvt_f32_f16_sdwa v47, v3 dst_sel:DWORD dst_unused:UNUSED_PAD src0_sel:WORD_1
	ds_write_b128 v32, v[40:43] offset:24576
	ds_write_b128 v32, v[44:47] offset:24592
	s_waitcnt vmcnt(5)
	v_cvt_f32_f16_e32 v40, v4
	v_cvt_f32_f16_sdwa v41, v4 dst_sel:DWORD dst_unused:UNUSED_PAD src0_sel:WORD_1
	v_cvt_f32_f16_e32 v42, v5
	v_cvt_f32_f16_sdwa v43, v5 dst_sel:DWORD dst_unused:UNUSED_PAD src0_sel:WORD_1
	v_cvt_f32_f16_e32 v44, v6
	v_cvt_f32_f16_sdwa v45, v6 dst_sel:DWORD dst_unused:UNUSED_PAD src0_sel:WORD_1
	v_cvt_f32_f16_e32 v46, v7
	v_cvt_f32_f16_sdwa v47, v7 dst_sel:DWORD dst_unused:UNUSED_PAD src0_sel:WORD_1
	ds_write_b128 v33, v[40:43] offset:24576
	ds_write_b128 v33, v[44:47] offset:24592
	s_waitcnt vmcnt(4)
	v_cvt_f32_f16_e32 v40, v8
	v_cvt_f32_f16_sdwa v41, v8 dst_sel:DWORD dst_unused:UNUSED_PAD src0_sel:WORD_1
	v_cvt_f32_f16_e32 v42, v9
	v_cvt_f32_f16_sdwa v43, v9 dst_sel:DWORD dst_unused:UNUSED_PAD src0_sel:WORD_1
	v_cvt_f32_f16_e32 v44, v10
	v_cvt_f32_f16_sdwa v45, v10 dst_sel:DWORD dst_unused:UNUSED_PAD src0_sel:WORD_1
	v_cvt_f32_f16_e32 v46, v11
	v_cvt_f32_f16_sdwa v47, v11 dst_sel:DWORD dst_unused:UNUSED_PAD src0_sel:WORD_1
	ds_write_b128 v34, v[40:43] offset:24576
	ds_write_b128 v34, v[44:47] offset:24592
	s_add_i32 s26, s26, 16
	s_waitcnt lgkmcnt(0)
	s_barrier
; DI void scan_item(const Params& p, int item, char* smem) {
;     ...
;   auto gload = [&](int ci) {
; #pragma unroll
;     for (int i = 0; i < 3; i++) {
;       int id = tid + i * 256;
;       int st = id / 48, rem = id % 48, vec = rem >> 3, part = rem & 7;
;       int t = tof(ci * 16 + st);
;       int vi = vec < 3 ? vec : vec + 3 * dir;
;       rg_[i] = *(const u32x4*)(SIb + ((long)t * 9 + vi) * 64 + part * 8);
;     }
;   };
;     ...
;   auto ldstep = [&](const float* b) {
;     StepIn x;
;     x.r = *(const f32x4v*)(b + cg4); x.k = *(const f32x4v*)(b + 64 + cg4); x.v = b[voff];
;     x.w = *(const f32x4v*)(b + 192 + cg4); x.d = *(const f32x4v*)(b + 256 + cg4); x.b = *(const f32x4v*)(b + 320 + cg4);
;     return x;
;   };
;   for (int ci = 0; ci < nch; ci++) {
;     if (ci + 1 < nch) gload(ci + 1);
;     const float* base = sIn + (ci & 1) * 16 * 6 * 64;
;     float ykeep = 0.f;
;     StepIn cur = ldstep(base);
; #pragma unroll
;     for (int st = 0; st < 16; st++) {
;       StepIn nxt = cur;
;       if (st + 1 < 16) nxt = ldstep(base + (st + 1) * 6 * 64);
;       __builtin_amdgcn_sched_barrier(0);
;       f32x2 ra = {cur.r.x, cur.r.y}, rb = {cur.r.z, cur.r.w}, ka = {cur.k.x, cur.k.y}, kb = {cur.k.z, cur.k.w};
;       f32x2 wa = {cur.w.x, cur.w.y}, wb = {cur.w.z, cur.w.w}, da = {cur.d.x, cur.d.y}, db = {cur.d.z, cur.d.w};
;       f32x2 ba = {cur.b.x, cur.b.y}, bb2 = {cur.b.z, cur.b.w};
;       f32x2 pp = Sa * ka + Sb * kb;
;       float sa = allreduce16(pp.x + pp.y);
;       f32x2 vv2 = {cur.v, cur.v};
;       f32x2 sa2 = {sa, sa};
;       Sa = (Sa * wa + vv2 * da) - sa2 * ba;
;       Sb = (Sb * wb + vv2 * db) - sa2 * bb2;
;       f32x2 yy = Sa * ra + Sb * rb;
;       float y = allreduce16(yy.x + yy.y);
;       ykeep = (l16 == st) ? y : ykeep;
;       cur = nxt;
;     }
	ds_read_b128 v[72:75], v49 offset:24832
	ds_read_b32 v88, v50 offset:25088
	ds_read_b128 v[80:83], v49 offset:25600
	ds_read_b128 v[76:79], v49 offset:25344
	ds_read_b128 v[84:87], v49 offset:25856
	ds_read_b128 v[68:71], v49 offset:24576
	ds_read_b128 v[100:103], v49 offset:26368
	ds_read_b32 v116, v50 offset:26624
	ds_read_b128 v[108:111], v49 offset:27136
	ds_read_b128 v[104:107], v49 offset:26880
	ds_read_b128 v[112:115], v49 offset:27392
	ds_read_b128 v[96:99], v49 offset:26112
	s_add_i32 s72, s26, 32
	s_mov_b32 vcc_hi, 0x4c3800
	s_cmp_eq_u32 s72, 0x100
	s_cselect_b32 vcc_lo, vcc_hi, 0xffffb800
	s_cmp_lg_u32 s36, 0
	s_cselect_b32 vcc_lo, 0x4800, vcc_lo
	s_cmp_ge_u32 s72, 0x1100
	s_cselect_b32 vcc_lo, 0, vcc_lo
	s_ashr_i32 vcc_hi, vcc_lo, 31
	v_lshl_add_u64 v[236:237], v[236:237], 0, vcc
	v_lshl_add_u64 v[238:239], v[238:239], 0, vcc
	v_lshl_add_u64 v[240:241], v[240:241], 0, vcc
	global_load_dwordx4 v[0:3], v[236:237], off
	global_load_dwordx4 v[4:7], v[238:239], off
	global_load_dwordx4 v[8:11], v[240:241], off
	s_waitcnt lgkmcnt(6)
	ds_read_b128 v[122:125], v49 offset:27904
	ds_read_b32 v138, v50 offset:28160
	ds_read_b128 v[130:133], v49 offset:28672
	ds_read_b128 v[126:129], v49 offset:28416
	ds_read_b128 v[134:137], v49 offset:28928
	ds_read_b128 v[118:121], v49 offset:27648
	v_pk_mul_f32 v[56:57], v[90:91], v[72:73]
	v_pk_mul_f32 v[60:61], v[88:89], v[80:81] op_sel_hi:[0,1]
	v_pk_fma_f32 v[56:57], v[92:93], v[74:75], v[56:57]
	v_pk_mul_f32 v[62:63], v[88:89], v[82:83] op_sel_hi:[0,1]
	v_add_f32_e32 v58, v56, v57
	v_pk_fma_f32 v[60:61], v[90:91], v[76:77], v[60:61]
	v_pk_fma_f32 v[62:63], v[92:93], v[78:79], v[62:63]
	v_add_f32_dpp v58, v58, v58 quad_perm:[1,0,3,2] row_mask:0xf bank_mask:0xf bound_ctrl:1
	s_nop 1
	v_add_f32_dpp v58, v58, v58 quad_perm:[2,3,0,1] row_mask:0xf bank_mask:0xf bound_ctrl:1
	s_nop 1
	v_add_f32_dpp v58, v58, v58 row_half_mirror row_mask:0xf bank_mask:0xf bound_ctrl:1
	s_nop 1
	v_add_f32_dpp v58, v58, v58 row_mirror row_mask:0xf bank_mask:0xf bound_ctrl:1
	s_nop 0
	v_pk_fma_f32 v[90:91], v[84:85], v[58:59], v[60:61] op_sel_hi:[1,0,1] neg_lo:[1,0,0] neg_hi:[1,0,0]
	v_pk_fma_f32 v[92:93], v[86:87], v[58:59], v[62:63] op_sel_hi:[1,0,1] neg_lo:[1,0,0] neg_hi:[1,0,0]
	s_waitcnt lgkmcnt(6)
	ds_read_b128 v[144:147], v49 offset:29440
	ds_read_b32 v160, v50 offset:29696
	ds_read_b128 v[152:155], v49 offset:30208
	ds_read_b128 v[148:151], v49 offset:29952
	ds_read_b128 v[156:159], v49 offset:30464
	ds_read_b128 v[140:143], v49 offset:29184
	v_pk_mul_f32 v[56:57], v[90:91], v[100:101]
	v_pk_mul_f32 v[64:65], v[70:71], v[92:93]
	v_pk_fma_f32 v[56:57], v[92:93], v[102:103], v[56:57]
	v_pk_fma_f32 v[64:65], v[68:69], v[90:91], v[64:65]
	v_add_f32_e32 v58, v56, v57
	v_add_f32_e32 v66, v64, v65
	v_pk_mul_f32 v[60:61], v[116:117], v[108:109] op_sel_hi:[0,1]
	v_add_f32_dpp v58, v58, v58 quad_perm:[1,0,3,2] row_mask:0xf bank_mask:0xf bound_ctrl:1
	v_add_f32_dpp v66, v66, v66 quad_perm:[1,0,3,2] row_mask:0xf bank_mask:0xf bound_ctrl:1
	v_pk_fma_f32 v[60:61], v[90:91], v[104:105], v[60:61]
	v_add_f32_dpp v58, v58, v58 quad_perm:[2,3,0,1] row_mask:0xf bank_mask:0xf bound_ctrl:1
	v_add_f32_dpp v66, v66, v66 quad_perm:[2,3,0,1] row_mask:0xf bank_mask:0xf bound_ctrl:1
	v_pk_mul_f32 v[62:63], v[116:117], v[110:111] op_sel_hi:[0,1]
	v_add_f32_dpp v58, v58, v58 row_half_mirror row_mask:0xf bank_mask:0xf bound_ctrl:1
	v_add_f32_dpp v66, v66, v66 row_half_mirror row_mask:0xf bank_mask:0xf bound_ctrl:1
	v_pk_fma_f32 v[62:63], v[92:93], v[106:107], v[62:63]
	v_add_f32_dpp v58, v58, v58 row_mirror row_mask:0xf bank_mask:0xf bound_ctrl:1
	v_add_f32_dpp v66, v66, v66 row_mirror row_mask:0xf bank_mask:0xf bound_ctrl:1
	v_pk_fma_f32 v[90:91], v[112:113], v[58:59], v[60:61] op_sel_hi:[1,0,1] neg_lo:[1,0,0] neg_hi:[1,0,0]
	v_pk_fma_f32 v[92:93], v[114:115], v[58:59], v[62:63] op_sel_hi:[1,0,1] neg_lo:[1,0,0] neg_hi:[1,0,0]
	v_cndmask_b32_e64 v67, 0, v66, s[38:39]
	s_waitcnt lgkmcnt(6)
	ds_read_b128 v[72:75], v49 offset:30976
	ds_read_b32 v88, v50 offset:31232
	ds_read_b128 v[80:83], v49 offset:31744
	ds_read_b128 v[76:79], v49 offset:31488
	ds_read_b128 v[84:87], v49 offset:32000
	ds_read_b128 v[68:71], v49 offset:30720
	v_pk_mul_f32 v[56:57], v[90:91], v[122:123]
	v_pk_mul_f32 v[64:65], v[98:99], v[92:93]
	v_pk_fma_f32 v[56:57], v[92:93], v[124:125], v[56:57]
	v_pk_fma_f32 v[64:65], v[96:97], v[90:91], v[64:65]
	v_add_f32_e32 v58, v56, v57
	v_add_f32_e32 v66, v64, v65
	v_pk_mul_f32 v[60:61], v[138:139], v[130:131] op_sel_hi:[0,1]
	v_add_f32_dpp v58, v58, v58 quad_perm:[1,0,3,2] row_mask:0xf bank_mask:0xf bound_ctrl:1
	v_add_f32_dpp v66, v66, v66 quad_perm:[1,0,3,2] row_mask:0xf bank_mask:0xf bound_ctrl:1
	v_pk_fma_f32 v[60:61], v[90:91], v[126:127], v[60:61]
	v_add_f32_dpp v58, v58, v58 quad_perm:[2,3,0,1] row_mask:0xf bank_mask:0xf bound_ctrl:1
	v_add_f32_dpp v66, v66, v66 quad_perm:[2,3,0,1] row_mask:0xf bank_mask:0xf bound_ctrl:1
	v_pk_mul_f32 v[62:63], v[138:139], v[132:133] op_sel_hi:[0,1]
	v_add_f32_dpp v58, v58, v58 row_half_mirror row_mask:0xf bank_mask:0xf bound_ctrl:1
	v_add_f32_dpp v66, v66, v66 row_half_mirror row_mask:0xf bank_mask:0xf bound_ctrl:1
	v_pk_fma_f32 v[62:63], v[92:93], v[128:129], v[62:63]
	v_add_f32_dpp v58, v58, v58 row_mirror row_mask:0xf bank_mask:0xf bound_ctrl:1
	v_add_f32_dpp v66, v66, v66 row_mirror row_mask:0xf bank_mask:0xf bound_ctrl:1
	v_pk_fma_f32 v[90:91], v[134:135], v[58:59], v[60:61] op_sel_hi:[1,0,1] neg_lo:[1,0,0] neg_hi:[1,0,0]
	v_pk_fma_f32 v[92:93], v[136:137], v[58:59], v[62:63] op_sel_hi:[1,0,1] neg_lo:[1,0,0] neg_hi:[1,0,0]
	v_cndmask_b32_e64 v67, v67, v66, s[40:41]
	s_waitcnt lgkmcnt(6)
; DI void scan_item(const Params& p, int item, char* smem) {
;     ...
;   auto ldstep = [&](const float* b) {
;     StepIn x;
;     x.r = *(const f32x4v*)(b + cg4); x.k = *(const f32x4v*)(b + 64 + cg4); x.v = b[voff];
;     x.w = *(const f32x4v*)(b + 192 + cg4); x.d = *(const f32x4v*)(b + 256 + cg4); x.b = *(const f32x4v*)(b + 320 + cg4);
;     return x;
;   };
;   for (int ci = 0; ci < nch; ci++) {
;     if (ci + 1 < nch) gload(ci + 1);
;     const float* base = sIn + (ci & 1) * 16 * 6 * 64;
;     float ykeep = 0.f;
;     StepIn cur = ldstep(base);
; #pragma unroll
;     for (int st = 0; st < 16; st++) {
;       StepIn nxt = cur;
;       if (st + 1 < 16) nxt = ldstep(base + (st + 1) * 6 * 64);
;       __builtin_amdgcn_sched_barrier(0);
;       f32x2 ra = {cur.r.x, cur.r.y}, rb = {cur.r.z, cur.r.w}, ka = {cur.k.x, cur.k.y}, kb = {cur.k.z, cur.k.w};
;       f32x2 wa = {cur.w.x, cur.w.y}, wb = {cur.w.z, cur.w.w}, da = {cur.d.x, cur.d.y}, db = {cur.d.z, cur.d.w};
;       f32x2 ba = {cur.b.x, cur.b.y}, bb2 = {cur.b.z, cur.b.w};
;       f32x2 pp = Sa * ka + Sb * kb;
;       float sa = allreduce16(pp.x + pp.y);
;       f32x2 vv2 = {cur.v, cur.v};
;       f32x2 sa2 = {sa, sa};
;       Sa = (Sa * wa + vv2 * da) - sa2 * ba;
;       Sb = (Sb * wb + vv2 * db) - sa2 * bb2;
;       f32x2 yy = Sa * ra + Sb * rb;
;       float y = allreduce16(yy.x + yy.y);
;       ykeep = (l16 == st) ? y : ykeep;
;       cur = nxt;
;     }
	ds_read_b128 v[100:103], v49 offset:32512
	ds_read_b32 v116, v50 offset:32768
	ds_read_b128 v[108:111], v49 offset:33280
	ds_read_b128 v[104:107], v49 offset:33024
	ds_read_b128 v[112:115], v49 offset:33536
	ds_read_b128 v[96:99], v49 offset:32256
	v_pk_mul_f32 v[56:57], v[90:91], v[144:145]
	v_pk_mul_f32 v[64:65], v[120:121], v[92:93]
	v_pk_fma_f32 v[56:57], v[92:93], v[146:147], v[56:57]
	v_pk_fma_f32 v[64:65], v[118:119], v[90:91], v[64:65]
	v_add_f32_e32 v58, v56, v57
	v_add_f32_e32 v66, v64, v65
	v_pk_mul_f32 v[60:61], v[160:161], v[152:153] op_sel_hi:[0,1]
	v_add_f32_dpp v58, v58, v58 quad_perm:[1,0,3,2] row_mask:0xf bank_mask:0xf bound_ctrl:1
	v_add_f32_dpp v66, v66, v66 quad_perm:[1,0,3,2] row_mask:0xf bank_mask:0xf bound_ctrl:1
	v_pk_fma_f32 v[60:61], v[90:91], v[148:149], v[60:61]
	v_add_f32_dpp v58, v58, v58 quad_perm:[2,3,0,1] row_mask:0xf bank_mask:0xf bound_ctrl:1
	v_add_f32_dpp v66, v66, v66 quad_perm:[2,3,0,1] row_mask:0xf bank_mask:0xf bound_ctrl:1
	v_pk_mul_f32 v[62:63], v[160:161], v[154:155] op_sel_hi:[0,1]
	v_add_f32_dpp v58, v58, v58 row_half_mirror row_mask:0xf bank_mask:0xf bound_ctrl:1
	v_add_f32_dpp v66, v66, v66 row_half_mirror row_mask:0xf bank_mask:0xf bound_ctrl:1
	v_pk_fma_f32 v[62:63], v[92:93], v[150:151], v[62:63]
	v_add_f32_dpp v58, v58, v58 row_mirror row_mask:0xf bank_mask:0xf bound_ctrl:1
	v_add_f32_dpp v66, v66, v66 row_mirror row_mask:0xf bank_mask:0xf bound_ctrl:1
	v_pk_fma_f32 v[90:91], v[156:157], v[58:59], v[60:61] op_sel_hi:[1,0,1] neg_lo:[1,0,0] neg_hi:[1,0,0]
	v_pk_fma_f32 v[92:93], v[158:159], v[58:59], v[62:63] op_sel_hi:[1,0,1] neg_lo:[1,0,0] neg_hi:[1,0,0]
	v_cndmask_b32_e64 v67, v67, v66, s[42:43]
	s_waitcnt lgkmcnt(6)
	ds_read_b128 v[122:125], v49 offset:34048
	ds_read_b32 v138, v50 offset:34304
	ds_read_b128 v[130:133], v49 offset:34816
	ds_read_b128 v[126:129], v49 offset:34560
	ds_read_b128 v[134:137], v49 offset:35072
	ds_read_b128 v[118:121], v49 offset:33792
	v_pk_mul_f32 v[56:57], v[90:91], v[72:73]
	v_pk_mul_f32 v[64:65], v[142:143], v[92:93]
	v_pk_fma_f32 v[56:57], v[92:93], v[74:75], v[56:57]
	v_pk_fma_f32 v[64:65], v[140:141], v[90:91], v[64:65]
	v_add_f32_e32 v58, v56, v57
	v_add_f32_e32 v66, v64, v65
	v_pk_mul_f32 v[60:61], v[88:89], v[80:81] op_sel_hi:[0,1]
	v_add_f32_dpp v58, v58, v58 quad_perm:[1,0,3,2] row_mask:0xf bank_mask:0xf bound_ctrl:1
	v_add_f32_dpp v66, v66, v66 quad_perm:[1,0,3,2] row_mask:0xf bank_mask:0xf bound_ctrl:1
	v_pk_fma_f32 v[60:61], v[90:91], v[76:77], v[60:61]
	v_add_f32_dpp v58, v58, v58 quad_perm:[2,3,0,1] row_mask:0xf bank_mask:0xf bound_ctrl:1
	v_add_f32_dpp v66, v66, v66 quad_perm:[2,3,0,1] row_mask:0xf bank_mask:0xf bound_ctrl:1
	v_pk_mul_f32 v[62:63], v[88:89], v[82:83] op_sel_hi:[0,1]
	v_add_f32_dpp v58, v58, v58 row_half_mirror row_mask:0xf bank_mask:0xf bound_ctrl:1
	v_add_f32_dpp v66, v66, v66 row_half_mirror row_mask:0xf bank_mask:0xf bound_ctrl:1
	v_pk_fma_f32 v[62:63], v[92:93], v[78:79], v[62:63]
	v_add_f32_dpp v58, v58, v58 row_mirror row_mask:0xf bank_mask:0xf bound_ctrl:1
	v_add_f32_dpp v66, v66, v66 row_mirror row_mask:0xf bank_mask:0xf bound_ctrl:1
	v_pk_fma_f32 v[90:91], v[84:85], v[58:59], v[60:61] op_sel_hi:[1,0,1] neg_lo:[1,0,0] neg_hi:[1,0,0]
	v_pk_fma_f32 v[92:93], v[86:87], v[58:59], v[62:63] op_sel_hi:[1,0,1] neg_lo:[1,0,0] neg_hi:[1,0,0]
	v_cndmask_b32_e64 v67, v67, v66, s[44:45]
	s_waitcnt lgkmcnt(6)
	ds_read_b128 v[144:147], v49 offset:35584
	ds_read_b32 v160, v50 offset:35840
	ds_read_b128 v[152:155], v49 offset:36352
	ds_read_b128 v[148:151], v49 offset:36096
	ds_read_b128 v[156:159], v49 offset:36608
	ds_read_b128 v[140:143], v49 offset:35328
	v_pk_mul_f32 v[56:57], v[90:91], v[100:101]
	v_pk_mul_f32 v[64:65], v[70:71], v[92:93]
	v_pk_fma_f32 v[56:57], v[92:93], v[102:103], v[56:57]
	v_pk_fma_f32 v[64:65], v[68:69], v[90:91], v[64:65]
	v_add_f32_e32 v58, v56, v57
	v_add_f32_e32 v66, v64, v65
	v_pk_mul_f32 v[60:61], v[116:117], v[108:109] op_sel_hi:[0,1]
	v_add_f32_dpp v58, v58, v58 quad_perm:[1,0,3,2] row_mask:0xf bank_mask:0xf bound_ctrl:1
	v_add_f32_dpp v66, v66, v66 quad_perm:[1,0,3,2] row_mask:0xf bank_mask:0xf bound_ctrl:1
	v_pk_fma_f32 v[60:61], v[90:91], v[104:105], v[60:61]
	v_add_f32_dpp v58, v58, v58 quad_perm:[2,3,0,1] row_mask:0xf bank_mask:0xf bound_ctrl:1
	v_add_f32_dpp v66, v66, v66 quad_perm:[2,3,0,1] row_mask:0xf bank_mask:0xf bound_ctrl:1
	v_pk_mul_f32 v[62:63], v[116:117], v[110:111] op_sel_hi:[0,1]
	v_add_f32_dpp v58, v58, v58 row_half_mirror row_mask:0xf bank_mask:0xf bound_ctrl:1
	v_add_f32_dpp v66, v66, v66 row_half_mirror row_mask:0xf bank_mask:0xf bound_ctrl:1
	v_pk_fma_f32 v[62:63], v[92:93], v[106:107], v[62:63]
	v_add_f32_dpp v58, v58, v58 row_mirror row_mask:0xf bank_mask:0xf bound_ctrl:1
	v_add_f32_dpp v66, v66, v66 row_mirror row_mask:0xf bank_mask:0xf bound_ctrl:1
	v_pk_fma_f32 v[90:91], v[112:113], v[58:59], v[60:61] op_sel_hi:[1,0,1] neg_lo:[1,0,0] neg_hi:[1,0,0]
	v_pk_fma_f32 v[92:93], v[114:115], v[58:59], v[62:63] op_sel_hi:[1,0,1] neg_lo:[1,0,0] neg_hi:[1,0,0]
	v_cndmask_b32_e64 v67, v67, v66, s[46:47]
	s_waitcnt lgkmcnt(6)
; DI void scan_item(const Params& p, int item, char* smem) {
;     ...
;   auto ldstep = [&](const float* b) {
;     StepIn x;
;     x.r = *(const f32x4v*)(b + cg4); x.k = *(const f32x4v*)(b + 64 + cg4); x.v = b[voff];
;     x.w = *(const f32x4v*)(b + 192 + cg4); x.d = *(const f32x4v*)(b + 256 + cg4); x.b = *(const f32x4v*)(b + 320 + cg4);
;     return x;
;   };
;   for (int ci = 0; ci < nch; ci++) {
;     if (ci + 1 < nch) gload(ci + 1);
;     const float* base = sIn + (ci & 1) * 16 * 6 * 64;
;     float ykeep = 0.f;
;     StepIn cur = ldstep(base);
; #pragma unroll
;     for (int st = 0; st < 16; st++) {
;       StepIn nxt = cur;
;       if (st + 1 < 16) nxt = ldstep(base + (st + 1) * 6 * 64);
;       __builtin_amdgcn_sched_barrier(0);
;       f32x2 ra = {cur.r.x, cur.r.y}, rb = {cur.r.z, cur.r.w}, ka = {cur.k.x, cur.k.y}, kb = {cur.k.z, cur.k.w};
;       f32x2 wa = {cur.w.x, cur.w.y}, wb = {cur.w.z, cur.w.w}, da = {cur.d.x, cur.d.y}, db = {cur.d.z, cur.d.w};
;       f32x2 ba = {cur.b.x, cur.b.y}, bb2 = {cur.b.z, cur.b.w};
;       f32x2 pp = Sa * ka + Sb * kb;
;       float sa = allreduce16(pp.x + pp.y);
;       f32x2 vv2 = {cur.v, cur.v};
;       f32x2 sa2 = {sa, sa};
;       Sa = (Sa * wa + vv2 * da) - sa2 * ba;
;       Sb = (Sb * wb + vv2 * db) - sa2 * bb2;
;       f32x2 yy = Sa * ra + Sb * rb;
;       float y = allreduce16(yy.x + yy.y);
;       ykeep = (l16 == st) ? y : ykeep;
;       cur = nxt;
;     }
	ds_read_b128 v[72:75], v49 offset:37120
	ds_read_b32 v88, v50 offset:37376
	ds_read_b128 v[80:83], v49 offset:37888
	ds_read_b128 v[76:79], v49 offset:37632
	ds_read_b128 v[84:87], v49 offset:38144
	ds_read_b128 v[68:71], v49 offset:36864
	v_pk_mul_f32 v[56:57], v[90:91], v[122:123]
	v_pk_mul_f32 v[64:65], v[98:99], v[92:93]
	v_pk_fma_f32 v[56:57], v[92:93], v[124:125], v[56:57]
	v_pk_fma_f32 v[64:65], v[96:97], v[90:91], v[64:65]
	v_add_f32_e32 v58, v56, v57
	v_add_f32_e32 v66, v64, v65
	v_pk_mul_f32 v[60:61], v[138:139], v[130:131] op_sel_hi:[0,1]
	v_add_f32_dpp v58, v58, v58 quad_perm:[1,0,3,2] row_mask:0xf bank_mask:0xf bound_ctrl:1
	v_add_f32_dpp v66, v66, v66 quad_perm:[1,0,3,2] row_mask:0xf bank_mask:0xf bound_ctrl:1
	v_pk_fma_f32 v[60:61], v[90:91], v[126:127], v[60:61]
	v_add_f32_dpp v58, v58, v58 quad_perm:[2,3,0,1] row_mask:0xf bank_mask:0xf bound_ctrl:1
	v_add_f32_dpp v66, v66, v66 quad_perm:[2,3,0,1] row_mask:0xf bank_mask:0xf bound_ctrl:1
	v_pk_mul_f32 v[62:63], v[138:139], v[132:133] op_sel_hi:[0,1]
	v_add_f32_dpp v58, v58, v58 row_half_mirror row_mask:0xf bank_mask:0xf bound_ctrl:1
	v_add_f32_dpp v66, v66, v66 row_half_mirror row_mask:0xf bank_mask:0xf bound_ctrl:1
	v_pk_fma_f32 v[62:63], v[92:93], v[128:129], v[62:63]
	v_add_f32_dpp v58, v58, v58 row_mirror row_mask:0xf bank_mask:0xf bound_ctrl:1
	v_add_f32_dpp v66, v66, v66 row_mirror row_mask:0xf bank_mask:0xf bound_ctrl:1
	v_pk_fma_f32 v[90:91], v[134:135], v[58:59], v[60:61] op_sel_hi:[1,0,1] neg_lo:[1,0,0] neg_hi:[1,0,0]
	v_pk_fma_f32 v[92:93], v[136:137], v[58:59], v[62:63] op_sel_hi:[1,0,1] neg_lo:[1,0,0] neg_hi:[1,0,0]
	v_cndmask_b32_e64 v67, v67, v66, s[48:49]
	s_waitcnt lgkmcnt(6)
	ds_read_b128 v[100:103], v49 offset:38656
	ds_read_b32 v116, v50 offset:38912
	ds_read_b128 v[108:111], v49 offset:39424
	ds_read_b128 v[104:107], v49 offset:39168
	ds_read_b128 v[112:115], v49 offset:39680
	ds_read_b128 v[96:99], v49 offset:38400
	v_pk_mul_f32 v[56:57], v[90:91], v[144:145]
	v_pk_mul_f32 v[64:65], v[120:121], v[92:93]
	v_pk_fma_f32 v[56:57], v[92:93], v[146:147], v[56:57]
	v_pk_fma_f32 v[64:65], v[118:119], v[90:91], v[64:65]
	v_add_f32_e32 v58, v56, v57
	v_add_f32_e32 v66, v64, v65
	v_pk_mul_f32 v[60:61], v[160:161], v[152:153] op_sel_hi:[0,1]
	v_add_f32_dpp v58, v58, v58 quad_perm:[1,0,3,2] row_mask:0xf bank_mask:0xf bound_ctrl:1
	v_add_f32_dpp v66, v66, v66 quad_perm:[1,0,3,2] row_mask:0xf bank_mask:0xf bound_ctrl:1
	v_pk_fma_f32 v[60:61], v[90:91], v[148:149], v[60:61]
	v_add_f32_dpp v58, v58, v58 quad_perm:[2,3,0,1] row_mask:0xf bank_mask:0xf bound_ctrl:1
	v_add_f32_dpp v66, v66, v66 quad_perm:[2,3,0,1] row_mask:0xf bank_mask:0xf bound_ctrl:1
	v_pk_mul_f32 v[62:63], v[160:161], v[154:155] op_sel_hi:[0,1]
	v_add_f32_dpp v58, v58, v58 row_half_mirror row_mask:0xf bank_mask:0xf bound_ctrl:1
	v_add_f32_dpp v66, v66, v66 row_half_mirror row_mask:0xf bank_mask:0xf bound_ctrl:1
	v_pk_fma_f32 v[62:63], v[92:93], v[150:151], v[62:63]
	v_add_f32_dpp v58, v58, v58 row_mirror row_mask:0xf bank_mask:0xf bound_ctrl:1
	v_add_f32_dpp v66, v66, v66 row_mirror row_mask:0xf bank_mask:0xf bound_ctrl:1
	v_pk_fma_f32 v[90:91], v[156:157], v[58:59], v[60:61] op_sel_hi:[1,0,1] neg_lo:[1,0,0] neg_hi:[1,0,0]
	v_pk_fma_f32 v[92:93], v[158:159], v[58:59], v[62:63] op_sel_hi:[1,0,1] neg_lo:[1,0,0] neg_hi:[1,0,0]
	v_cndmask_b32_e64 v67, v67, v66, s[50:51]
	s_waitcnt lgkmcnt(6)
	ds_read_b128 v[122:125], v49 offset:40192
	ds_read_b32 v138, v50 offset:40448
	ds_read_b128 v[130:133], v49 offset:40960
	ds_read_b128 v[126:129], v49 offset:40704
	ds_read_b128 v[134:137], v49 offset:41216
	ds_read_b128 v[118:121], v49 offset:39936
	v_pk_mul_f32 v[56:57], v[90:91], v[72:73]
	v_pk_mul_f32 v[64:65], v[142:143], v[92:93]
	v_pk_fma_f32 v[56:57], v[92:93], v[74:75], v[56:57]
	v_pk_fma_f32 v[64:65], v[140:141], v[90:91], v[64:65]
	v_add_f32_e32 v58, v56, v57
	v_add_f32_e32 v66, v64, v65
	v_pk_mul_f32 v[60:61], v[88:89], v[80:81] op_sel_hi:[0,1]
	v_add_f32_dpp v58, v58, v58 quad_perm:[1,0,3,2] row_mask:0xf bank_mask:0xf bound_ctrl:1
	v_add_f32_dpp v66, v66, v66 quad_perm:[1,0,3,2] row_mask:0xf bank_mask:0xf bound_ctrl:1
	v_pk_fma_f32 v[60:61], v[90:91], v[76:77], v[60:61]
	v_add_f32_dpp v58, v58, v58 quad_perm:[2,3,0,1] row_mask:0xf bank_mask:0xf bound_ctrl:1
	v_add_f32_dpp v66, v66, v66 quad_perm:[2,3,0,1] row_mask:0xf bank_mask:0xf bound_ctrl:1
	v_pk_mul_f32 v[62:63], v[88:89], v[82:83] op_sel_hi:[0,1]
	v_add_f32_dpp v58, v58, v58 row_half_mirror row_mask:0xf bank_mask:0xf bound_ctrl:1
	v_add_f32_dpp v66, v66, v66 row_half_mirror row_mask:0xf bank_mask:0xf bound_ctrl:1
	v_pk_fma_f32 v[62:63], v[92:93], v[78:79], v[62:63]
	v_add_f32_dpp v58, v58, v58 row_mirror row_mask:0xf bank_mask:0xf bound_ctrl:1
	v_add_f32_dpp v66, v66, v66 row_mirror row_mask:0xf bank_mask:0xf bound_ctrl:1
	v_pk_fma_f32 v[90:91], v[84:85], v[58:59], v[60:61] op_sel_hi:[1,0,1] neg_lo:[1,0,0] neg_hi:[1,0,0]
	v_pk_fma_f32 v[92:93], v[86:87], v[58:59], v[62:63] op_sel_hi:[1,0,1] neg_lo:[1,0,0] neg_hi:[1,0,0]
	v_cndmask_b32_e64 v67, v67, v66, s[52:53]
	s_waitcnt lgkmcnt(6)
; DI void scan_item(const Params& p, int item, char* smem) {
;     ...
;   auto ldstep = [&](const float* b) {
;     StepIn x;
;     x.r = *(const f32x4v*)(b + cg4); x.k = *(const f32x4v*)(b + 64 + cg4); x.v = b[voff];
;     x.w = *(const f32x4v*)(b + 192 + cg4); x.d = *(const f32x4v*)(b + 256 + cg4); x.b = *(const f32x4v*)(b + 320 + cg4);
;     return x;
;   };
;   for (int ci = 0; ci < nch; ci++) {
;     if (ci + 1 < nch) gload(ci + 1);
;     const float* base = sIn + (ci & 1) * 16 * 6 * 64;
;     float ykeep = 0.f;
;     StepIn cur = ldstep(base);
; #pragma unroll
;     for (int st = 0; st < 16; st++) {
;       StepIn nxt = cur;
;       if (st + 1 < 16) nxt = ldstep(base + (st + 1) * 6 * 64);
;       __builtin_amdgcn_sched_barrier(0);
;       f32x2 ra = {cur.r.x, cur.r.y}, rb = {cur.r.z, cur.r.w}, ka = {cur.k.x, cur.k.y}, kb = {cur.k.z, cur.k.w};
;       f32x2 wa = {cur.w.x, cur.w.y}, wb = {cur.w.z, cur.w.w}, da = {cur.d.x, cur.d.y}, db = {cur.d.z, cur.d.w};
;       f32x2 ba = {cur.b.x, cur.b.y}, bb2 = {cur.b.z, cur.b.w};
;       f32x2 pp = Sa * ka + Sb * kb;
;       float sa = allreduce16(pp.x + pp.y);
;       f32x2 vv2 = {cur.v, cur.v};
;       f32x2 sa2 = {sa, sa};
;       Sa = (Sa * wa + vv2 * da) - sa2 * ba;
;       Sb = (Sb * wb + vv2 * db) - sa2 * bb2;
;       f32x2 yy = Sa * ra + Sb * rb;
;       float y = allreduce16(yy.x + yy.y);
;       ykeep = (l16 == st) ? y : ykeep;
;       cur = nxt;
;     }
	ds_read_b128 v[144:147], v49 offset:41728
	ds_read_b32 v160, v50 offset:41984
	ds_read_b128 v[152:155], v49 offset:42496
	ds_read_b128 v[148:151], v49 offset:42240
	ds_read_b128 v[156:159], v49 offset:42752
	ds_read_b128 v[140:143], v49 offset:41472
	v_pk_mul_f32 v[56:57], v[90:91], v[100:101]
	v_pk_mul_f32 v[64:65], v[70:71], v[92:93]
	v_pk_fma_f32 v[56:57], v[92:93], v[102:103], v[56:57]
	v_pk_fma_f32 v[64:65], v[68:69], v[90:91], v[64:65]
	v_add_f32_e32 v58, v56, v57
	v_add_f32_e32 v66, v64, v65
	v_pk_mul_f32 v[60:61], v[116:117], v[108:109] op_sel_hi:[0,1]
	v_add_f32_dpp v58, v58, v58 quad_perm:[1,0,3,2] row_mask:0xf bank_mask:0xf bound_ctrl:1
	v_add_f32_dpp v66, v66, v66 quad_perm:[1,0,3,2] row_mask:0xf bank_mask:0xf bound_ctrl:1
	v_pk_fma_f32 v[60:61], v[90:91], v[104:105], v[60:61]
	v_add_f32_dpp v58, v58, v58 quad_perm:[2,3,0,1] row_mask:0xf bank_mask:0xf bound_ctrl:1
	v_add_f32_dpp v66, v66, v66 quad_perm:[2,3,0,1] row_mask:0xf bank_mask:0xf bound_ctrl:1
	v_pk_mul_f32 v[62:63], v[116:117], v[110:111] op_sel_hi:[0,1]
	v_add_f32_dpp v58, v58, v58 row_half_mirror row_mask:0xf bank_mask:0xf bound_ctrl:1
	v_add_f32_dpp v66, v66, v66 row_half_mirror row_mask:0xf bank_mask:0xf bound_ctrl:1
	v_pk_fma_f32 v[62:63], v[92:93], v[106:107], v[62:63]
	v_add_f32_dpp v58, v58, v58 row_mirror row_mask:0xf bank_mask:0xf bound_ctrl:1
	v_add_f32_dpp v66, v66, v66 row_mirror row_mask:0xf bank_mask:0xf bound_ctrl:1
	v_pk_fma_f32 v[90:91], v[112:113], v[58:59], v[60:61] op_sel_hi:[1,0,1] neg_lo:[1,0,0] neg_hi:[1,0,0]
	v_pk_fma_f32 v[92:93], v[114:115], v[58:59], v[62:63] op_sel_hi:[1,0,1] neg_lo:[1,0,0] neg_hi:[1,0,0]
	v_cndmask_b32_e64 v67, v67, v66, s[54:55]
	s_waitcnt lgkmcnt(6)
	ds_read_b128 v[72:75], v49 offset:43264
	ds_read_b32 v88, v50 offset:43520
	ds_read_b128 v[80:83], v49 offset:44032
	ds_read_b128 v[76:79], v49 offset:43776
	ds_read_b128 v[84:87], v49 offset:44288
	ds_read_b128 v[68:71], v49 offset:43008
	v_pk_mul_f32 v[56:57], v[90:91], v[122:123]
	v_pk_mul_f32 v[64:65], v[98:99], v[92:93]
	v_pk_fma_f32 v[56:57], v[92:93], v[124:125], v[56:57]
	v_pk_fma_f32 v[64:65], v[96:97], v[90:91], v[64:65]
	v_add_f32_e32 v58, v56, v57
	v_add_f32_e32 v66, v64, v65
	v_pk_mul_f32 v[60:61], v[138:139], v[130:131] op_sel_hi:[0,1]
	v_add_f32_dpp v58, v58, v58 quad_perm:[1,0,3,2] row_mask:0xf bank_mask:0xf bound_ctrl:1
	v_add_f32_dpp v66, v66, v66 quad_perm:[1,0,3,2] row_mask:0xf bank_mask:0xf bound_ctrl:1
	v_pk_fma_f32 v[60:61], v[90:91], v[126:127], v[60:61]
	v_add_f32_dpp v58, v58, v58 quad_perm:[2,3,0,1] row_mask:0xf bank_mask:0xf bound_ctrl:1
	v_add_f32_dpp v66, v66, v66 quad_perm:[2,3,0,1] row_mask:0xf bank_mask:0xf bound_ctrl:1
	v_pk_mul_f32 v[62:63], v[138:139], v[132:133] op_sel_hi:[0,1]
	v_add_f32_dpp v58, v58, v58 row_half_mirror row_mask:0xf bank_mask:0xf bound_ctrl:1
	v_add_f32_dpp v66, v66, v66 row_half_mirror row_mask:0xf bank_mask:0xf bound_ctrl:1
	v_pk_fma_f32 v[62:63], v[92:93], v[128:129], v[62:63]
	v_add_f32_dpp v58, v58, v58 row_mirror row_mask:0xf bank_mask:0xf bound_ctrl:1
	v_add_f32_dpp v66, v66, v66 row_mirror row_mask:0xf bank_mask:0xf bound_ctrl:1
	v_pk_fma_f32 v[90:91], v[134:135], v[58:59], v[60:61] op_sel_hi:[1,0,1] neg_lo:[1,0,0] neg_hi:[1,0,0]
	v_pk_fma_f32 v[92:93], v[136:137], v[58:59], v[62:63] op_sel_hi:[1,0,1] neg_lo:[1,0,0] neg_hi:[1,0,0]
	v_cndmask_b32_e64 v67, v67, v66, s[56:57]
	s_waitcnt lgkmcnt(6)
	ds_read_b128 v[100:103], v49 offset:44800
	ds_read_b32 v116, v50 offset:45056
	ds_read_b128 v[108:111], v49 offset:45568
	ds_read_b128 v[104:107], v49 offset:45312
	ds_read_b128 v[112:115], v49 offset:45824
	ds_read_b128 v[96:99], v49 offset:44544
	v_pk_mul_f32 v[56:57], v[90:91], v[144:145]
	v_pk_mul_f32 v[64:65], v[120:121], v[92:93]
	v_pk_fma_f32 v[56:57], v[92:93], v[146:147], v[56:57]
	v_pk_fma_f32 v[64:65], v[118:119], v[90:91], v[64:65]
	v_add_f32_e32 v58, v56, v57
	v_add_f32_e32 v66, v64, v65
	v_pk_mul_f32 v[60:61], v[160:161], v[152:153] op_sel_hi:[0,1]
	v_add_f32_dpp v58, v58, v58 quad_perm:[1,0,3,2] row_mask:0xf bank_mask:0xf bound_ctrl:1
	v_add_f32_dpp v66, v66, v66 quad_perm:[1,0,3,2] row_mask:0xf bank_mask:0xf bound_ctrl:1
	v_pk_fma_f32 v[60:61], v[90:91], v[148:149], v[60:61]
	v_add_f32_dpp v58, v58, v58 quad_perm:[2,3,0,1] row_mask:0xf bank_mask:0xf bound_ctrl:1
	v_add_f32_dpp v66, v66, v66 quad_perm:[2,3,0,1] row_mask:0xf bank_mask:0xf bound_ctrl:1
	v_pk_mul_f32 v[62:63], v[160:161], v[154:155] op_sel_hi:[0,1]
	v_add_f32_dpp v58, v58, v58 row_half_mirror row_mask:0xf bank_mask:0xf bound_ctrl:1
	v_add_f32_dpp v66, v66, v66 row_half_mirror row_mask:0xf bank_mask:0xf bound_ctrl:1
	v_pk_fma_f32 v[62:63], v[92:93], v[150:151], v[62:63]
	v_add_f32_dpp v58, v58, v58 row_mirror row_mask:0xf bank_mask:0xf bound_ctrl:1
	v_add_f32_dpp v66, v66, v66 row_mirror row_mask:0xf bank_mask:0xf bound_ctrl:1
	v_pk_fma_f32 v[90:91], v[156:157], v[58:59], v[60:61] op_sel_hi:[1,0,1] neg_lo:[1,0,0] neg_hi:[1,0,0]
	v_pk_fma_f32 v[92:93], v[158:159], v[58:59], v[62:63] op_sel_hi:[1,0,1] neg_lo:[1,0,0] neg_hi:[1,0,0]
	v_cndmask_b32_e64 v67, v67, v66, s[58:59]
	s_waitcnt lgkmcnt(6)
; DI void scan_item(const Params& p, int item, char* smem) {
;     ...
;   auto ldstep = [&](const float* b) {
;     StepIn x;
;     x.r = *(const f32x4v*)(b + cg4); x.k = *(const f32x4v*)(b + 64 + cg4); x.v = b[voff];
;     x.w = *(const f32x4v*)(b + 192 + cg4); x.d = *(const f32x4v*)(b + 256 + cg4); x.b = *(const f32x4v*)(b + 320 + cg4);
;     return x;
;   };
;   for (int ci = 0; ci < nch; ci++) {
;     if (ci + 1 < nch) gload(ci + 1);
;     const float* base = sIn + (ci & 1) * 16 * 6 * 64;
;     float ykeep = 0.f;
;     StepIn cur = ldstep(base);
; #pragma unroll
;     for (int st = 0; st < 16; st++) {
;       StepIn nxt = cur;
;       if (st + 1 < 16) nxt = ldstep(base + (st + 1) * 6 * 64);
;       __builtin_amdgcn_sched_barrier(0);
;       f32x2 ra = {cur.r.x, cur.r.y}, rb = {cur.r.z, cur.r.w}, ka = {cur.k.x, cur.k.y}, kb = {cur.k.z, cur.k.w};
;       f32x2 wa = {cur.w.x, cur.w.y}, wb = {cur.w.z, cur.w.w}, da = {cur.d.x, cur.d.y}, db = {cur.d.z, cur.d.w};
;       f32x2 ba = {cur.b.x, cur.b.y}, bb2 = {cur.b.z, cur.b.w};
;       f32x2 pp = Sa * ka + Sb * kb;
;       float sa = allreduce16(pp.x + pp.y);
;       f32x2 vv2 = {cur.v, cur.v};
;       f32x2 sa2 = {sa, sa};
;       Sa = (Sa * wa + vv2 * da) - sa2 * ba;
;       Sb = (Sb * wb + vv2 * db) - sa2 * bb2;
;       f32x2 yy = Sa * ra + Sb * rb;
;       float y = allreduce16(yy.x + yy.y);
;       ykeep = (l16 == st) ? y : ykeep;
;       cur = nxt;
;     }
	ds_read_b128 v[122:125], v49 offset:46336
	ds_read_b32 v138, v50 offset:46592
	ds_read_b128 v[130:133], v49 offset:47104
	ds_read_b128 v[126:129], v49 offset:46848
	ds_read_b128 v[134:137], v49 offset:47360
	ds_read_b128 v[118:121], v49 offset:46080
	v_pk_mul_f32 v[56:57], v[90:91], v[72:73]
	v_pk_mul_f32 v[64:65], v[142:143], v[92:93]
	v_pk_fma_f32 v[56:57], v[92:93], v[74:75], v[56:57]
	v_pk_fma_f32 v[64:65], v[140:141], v[90:91], v[64:65]
	v_add_f32_e32 v58, v56, v57
	v_add_f32_e32 v66, v64, v65
	v_pk_mul_f32 v[60:61], v[88:89], v[80:81] op_sel_hi:[0,1]
	v_add_f32_dpp v58, v58, v58 quad_perm:[1,0,3,2] row_mask:0xf bank_mask:0xf bound_ctrl:1
	v_add_f32_dpp v66, v66, v66 quad_perm:[1,0,3,2] row_mask:0xf bank_mask:0xf bound_ctrl:1
	v_pk_fma_f32 v[60:61], v[90:91], v[76:77], v[60:61]
	v_add_f32_dpp v58, v58, v58 quad_perm:[2,3,0,1] row_mask:0xf bank_mask:0xf bound_ctrl:1
	v_add_f32_dpp v66, v66, v66 quad_perm:[2,3,0,1] row_mask:0xf bank_mask:0xf bound_ctrl:1
	v_pk_mul_f32 v[62:63], v[88:89], v[82:83] op_sel_hi:[0,1]
	v_add_f32_dpp v58, v58, v58 row_half_mirror row_mask:0xf bank_mask:0xf bound_ctrl:1
	v_add_f32_dpp v66, v66, v66 row_half_mirror row_mask:0xf bank_mask:0xf bound_ctrl:1
	v_pk_fma_f32 v[62:63], v[92:93], v[78:79], v[62:63]
	v_add_f32_dpp v58, v58, v58 row_mirror row_mask:0xf bank_mask:0xf bound_ctrl:1
	v_add_f32_dpp v66, v66, v66 row_mirror row_mask:0xf bank_mask:0xf bound_ctrl:1
	v_pk_fma_f32 v[90:91], v[84:85], v[58:59], v[60:61] op_sel_hi:[1,0,1] neg_lo:[1,0,0] neg_hi:[1,0,0]
	v_pk_fma_f32 v[92:93], v[86:87], v[58:59], v[62:63] op_sel_hi:[1,0,1] neg_lo:[1,0,0] neg_hi:[1,0,0]
	v_cndmask_b32_e64 v67, v67, v66, s[60:61]
	s_waitcnt lgkmcnt(6)
	ds_read_b128 v[144:147], v49 offset:47872
	ds_read_b32 v160, v50 offset:48128
	ds_read_b128 v[152:155], v49 offset:48640
	ds_read_b128 v[148:151], v49 offset:48384
	ds_read_b128 v[156:159], v49 offset:48896
	ds_read_b128 v[140:143], v49 offset:47616
	v_pk_mul_f32 v[56:57], v[90:91], v[100:101]
	v_pk_mul_f32 v[64:65], v[70:71], v[92:93]
	v_pk_fma_f32 v[56:57], v[92:93], v[102:103], v[56:57]
	v_pk_fma_f32 v[64:65], v[68:69], v[90:91], v[64:65]
	v_add_f32_e32 v58, v56, v57
	v_add_f32_e32 v66, v64, v65
	v_pk_mul_f32 v[60:61], v[116:117], v[108:109] op_sel_hi:[0,1]
	v_add_f32_dpp v58, v58, v58 quad_perm:[1,0,3,2] row_mask:0xf bank_mask:0xf bound_ctrl:1
	v_add_f32_dpp v66, v66, v66 quad_perm:[1,0,3,2] row_mask:0xf bank_mask:0xf bound_ctrl:1
	v_pk_fma_f32 v[60:61], v[90:91], v[104:105], v[60:61]
	v_add_f32_dpp v58, v58, v58 quad_perm:[2,3,0,1] row_mask:0xf bank_mask:0xf bound_ctrl:1
	v_add_f32_dpp v66, v66, v66 quad_perm:[2,3,0,1] row_mask:0xf bank_mask:0xf bound_ctrl:1
	v_pk_mul_f32 v[62:63], v[116:117], v[110:111] op_sel_hi:[0,1]
	v_add_f32_dpp v58, v58, v58 row_half_mirror row_mask:0xf bank_mask:0xf bound_ctrl:1
	v_add_f32_dpp v66, v66, v66 row_half_mirror row_mask:0xf bank_mask:0xf bound_ctrl:1
	v_pk_fma_f32 v[62:63], v[92:93], v[106:107], v[62:63]
	v_add_f32_dpp v58, v58, v58 row_mirror row_mask:0xf bank_mask:0xf bound_ctrl:1
	v_add_f32_dpp v66, v66, v66 row_mirror row_mask:0xf bank_mask:0xf bound_ctrl:1
	v_pk_fma_f32 v[90:91], v[112:113], v[58:59], v[60:61] op_sel_hi:[1,0,1] neg_lo:[1,0,0] neg_hi:[1,0,0]
	v_pk_fma_f32 v[92:93], v[114:115], v[58:59], v[62:63] op_sel_hi:[1,0,1] neg_lo:[1,0,0] neg_hi:[1,0,0]
	v_cndmask_b32_e64 v67, v67, v66, s[62:63]
	s_waitcnt lgkmcnt(6)
	v_pk_mul_f32 v[56:57], v[90:91], v[122:123]
	v_pk_mul_f32 v[64:65], v[98:99], v[92:93]
	v_pk_fma_f32 v[56:57], v[92:93], v[124:125], v[56:57]
	v_pk_fma_f32 v[64:65], v[96:97], v[90:91], v[64:65]
	v_add_f32_e32 v58, v56, v57
	v_add_f32_e32 v66, v64, v65
	v_pk_mul_f32 v[60:61], v[138:139], v[130:131] op_sel_hi:[0,1]
	v_add_f32_dpp v58, v58, v58 quad_perm:[1,0,3,2] row_mask:0xf bank_mask:0xf bound_ctrl:1
	v_add_f32_dpp v66, v66, v66 quad_perm:[1,0,3,2] row_mask:0xf bank_mask:0xf bound_ctrl:1
	v_pk_fma_f32 v[60:61], v[90:91], v[126:127], v[60:61]
	v_add_f32_dpp v58, v58, v58 quad_perm:[2,3,0,1] row_mask:0xf bank_mask:0xf bound_ctrl:1
	v_add_f32_dpp v66, v66, v66 quad_perm:[2,3,0,1] row_mask:0xf bank_mask:0xf bound_ctrl:1
	v_pk_mul_f32 v[62:63], v[138:139], v[132:133] op_sel_hi:[0,1]
	v_add_f32_dpp v58, v58, v58 row_half_mirror row_mask:0xf bank_mask:0xf bound_ctrl:1
	v_add_f32_dpp v66, v66, v66 row_half_mirror row_mask:0xf bank_mask:0xf bound_ctrl:1
	v_pk_fma_f32 v[62:63], v[92:93], v[128:129], v[62:63]
	v_add_f32_dpp v58, v58, v58 row_mirror row_mask:0xf bank_mask:0xf bound_ctrl:1
	v_add_f32_dpp v66, v66, v66 row_mirror row_mask:0xf bank_mask:0xf bound_ctrl:1
	v_pk_fma_f32 v[90:91], v[134:135], v[58:59], v[60:61] op_sel_hi:[1,0,1] neg_lo:[1,0,0] neg_hi:[1,0,0]
	v_pk_fma_f32 v[92:93], v[136:137], v[58:59], v[62:63] op_sel_hi:[1,0,1] neg_lo:[1,0,0] neg_hi:[1,0,0]
	v_cndmask_b32_e64 v67, v67, v66, s[64:65]
	s_waitcnt lgkmcnt(0)
; DI void scan_item(const Params& p, int item, char* smem) {
;     ...
;   auto lstore = [&](int buf) {
; #pragma unroll
;     for (int i = 0; i < 3; i++) {
;       int id = tid + i * 256;
;       int st = id / 48, rem = id % 48, vec = rem >> 3, part = rem & 7;
;       h8 hv = __builtin_bit_cast(h8, rg_[i]);
;       f8 fv = __builtin_convertvector(hv, f8);
;       float* d = sIn + ((buf * 16 + st) * 6 + vec) * 64 + part * 8;
;       *(f32x4v*)d = f32x4v{fv[0], fv[1], fv[2], fv[3]};
;       *(f32x4v*)(d + 4) = f32x4v{fv[4], fv[5], fv[6], fv[7]};
;     }
;   };
;     ...
;     for (int st = 0; st < 16; st++) {
;       StepIn nxt = cur;
;       if (st + 1 < 16) nxt = ldstep(base + (st + 1) * 6 * 64);
;       __builtin_amdgcn_sched_barrier(0);
;       f32x2 ra = {cur.r.x, cur.r.y}, rb = {cur.r.z, cur.r.w}, ka = {cur.k.x, cur.k.y}, kb = {cur.k.z, cur.k.w};
;       f32x2 wa = {cur.w.x, cur.w.y}, wb = {cur.w.z, cur.w.w}, da = {cur.d.x, cur.d.y}, db = {cur.d.z, cur.d.w};
;       f32x2 ba = {cur.b.x, cur.b.y}, bb2 = {cur.b.z, cur.b.w};
;       f32x2 pp = Sa * ka + Sb * kb;
;       float sa = allreduce16(pp.x + pp.y);
;       f32x2 vv2 = {cur.v, cur.v};
;       f32x2 sa2 = {sa, sa};
;       Sa = (Sa * wa + vv2 * da) - sa2 * ba;
;       Sb = (Sb * wb + vv2 * db) - sa2 * bb2;
;       f32x2 yy = Sa * ra + Sb * rb;
;       float y = allreduce16(yy.x + yy.y);
;       ykeep = (l16 == st) ? y : ykeep;
;       cur = nxt;
;     }
;     { _Float16 yh = (_Float16)ykeep; yb[(long)tof(ci * 16 + l16) * 256 + rowl] = __builtin_bit_cast(u16, yh); }
;     if (ci + 1 < nch) lstore((ci + 1) & 1);
;     __syncthreads();
;   }
	v_pk_mul_f32 v[56:57], v[90:91], v[144:145]
	v_pk_mul_f32 v[64:65], v[120:121], v[92:93]
	v_pk_fma_f32 v[56:57], v[92:93], v[146:147], v[56:57]
	v_pk_fma_f32 v[64:65], v[118:119], v[90:91], v[64:65]
	v_add_f32_e32 v58, v56, v57
	v_add_f32_e32 v66, v64, v65
	v_pk_mul_f32 v[60:61], v[160:161], v[152:153] op_sel_hi:[0,1]
	v_add_f32_dpp v58, v58, v58 quad_perm:[1,0,3,2] row_mask:0xf bank_mask:0xf bound_ctrl:1
	v_add_f32_dpp v66, v66, v66 quad_perm:[1,0,3,2] row_mask:0xf bank_mask:0xf bound_ctrl:1
	v_pk_fma_f32 v[60:61], v[90:91], v[148:149], v[60:61]
	v_add_f32_dpp v58, v58, v58 quad_perm:[2,3,0,1] row_mask:0xf bank_mask:0xf bound_ctrl:1
	v_add_f32_dpp v66, v66, v66 quad_perm:[2,3,0,1] row_mask:0xf bank_mask:0xf bound_ctrl:1
	v_pk_mul_f32 v[62:63], v[160:161], v[154:155] op_sel_hi:[0,1]
	v_add_f32_dpp v58, v58, v58 row_half_mirror row_mask:0xf bank_mask:0xf bound_ctrl:1
	v_add_f32_dpp v66, v66, v66 row_half_mirror row_mask:0xf bank_mask:0xf bound_ctrl:1
	v_pk_fma_f32 v[62:63], v[92:93], v[150:151], v[62:63]
	v_add_f32_dpp v58, v58, v58 row_mirror row_mask:0xf bank_mask:0xf bound_ctrl:1
	v_add_f32_dpp v66, v66, v66 row_mirror row_mask:0xf bank_mask:0xf bound_ctrl:1
	v_pk_fma_f32 v[90:91], v[156:157], v[58:59], v[60:61] op_sel_hi:[1,0,1] neg_lo:[1,0,0] neg_hi:[1,0,0]
	v_pk_fma_f32 v[92:93], v[158:159], v[58:59], v[62:63] op_sel_hi:[1,0,1] neg_lo:[1,0,0] neg_hi:[1,0,0]
	v_cndmask_b32_e64 v67, v67, v66, s[66:67]
	s_nop 0
	v_pk_mul_f32 v[64:65], v[142:143], v[92:93]
	v_pk_fma_f32 v[64:65], v[140:141], v[90:91], v[64:65]
	s_nop 0
	v_add_f32_e32 v66, v64, v65
	s_nop 0
	s_nop 0
	v_add_f32_dpp v66, v66, v66 quad_perm:[1,0,3,2] row_mask:0xf bank_mask:0xf bound_ctrl:1
	s_nop 0
	s_nop 0
	v_add_f32_dpp v66, v66, v66 quad_perm:[2,3,0,1] row_mask:0xf bank_mask:0xf bound_ctrl:1
	s_nop 0
	s_nop 0
	v_add_f32_dpp v66, v66, v66 row_half_mirror row_mask:0xf bank_mask:0xf bound_ctrl:1
	s_nop 1
	v_add_f32_dpp v66, v66, v66 row_mirror row_mask:0xf bank_mask:0xf bound_ctrl:1
	v_cndmask_b32_e64 v67, v67, v66, s[68:69]
	v_cvt_f16_f32_e32 v45, v67
	global_store_short v[242:243], v45, off
	s_add_i32 s12, s26, 16
	s_mov_b32 vcc_hi, 0x21e000
	s_cmp_eq_u32 s12, 0x100
	s_cselect_b32 vcc_lo, vcc_hi, 0xffffe000
	s_cmp_lg_u32 s36, 0
	s_cselect_b32 vcc_lo, 0x2000, vcc_lo
	s_ashr_i32 vcc_hi, vcc_lo, 31
	v_lshl_add_u64 v[242:243], v[242:243], 0, vcc
	s_waitcnt vmcnt(6)
	v_cvt_f32_f16_e32 v40, v162
	v_cvt_f32_f16_sdwa v41, v162 dst_sel:DWORD dst_unused:UNUSED_PAD src0_sel:WORD_1
	v_cvt_f32_f16_e32 v42, v163
	v_cvt_f32_f16_sdwa v43, v163 dst_sel:DWORD dst_unused:UNUSED_PAD src0_sel:WORD_1
	v_cvt_f32_f16_e32 v44, v164
	v_cvt_f32_f16_sdwa v45, v164 dst_sel:DWORD dst_unused:UNUSED_PAD src0_sel:WORD_1
	v_cvt_f32_f16_e32 v46, v165
	v_cvt_f32_f16_sdwa v47, v165 dst_sel:DWORD dst_unused:UNUSED_PAD src0_sel:WORD_1
	ds_write_b128 v32, v[40:43]
	ds_write_b128 v32, v[44:47] offset:16
	s_waitcnt vmcnt(5)
	v_cvt_f32_f16_e32 v40, v166
	v_cvt_f32_f16_sdwa v41, v166 dst_sel:DWORD dst_unused:UNUSED_PAD src0_sel:WORD_1
	v_cvt_f32_f16_e32 v42, v167
	v_cvt_f32_f16_sdwa v43, v167 dst_sel:DWORD dst_unused:UNUSED_PAD src0_sel:WORD_1
	v_cvt_f32_f16_e32 v44, v168
	v_cvt_f32_f16_sdwa v45, v168 dst_sel:DWORD dst_unused:UNUSED_PAD src0_sel:WORD_1
	v_cvt_f32_f16_e32 v46, v169
	v_cvt_f32_f16_sdwa v47, v169 dst_sel:DWORD dst_unused:UNUSED_PAD src0_sel:WORD_1
	ds_write_b128 v33, v[40:43]
	ds_write_b128 v33, v[44:47] offset:16
	s_waitcnt vmcnt(4)
	v_cvt_f32_f16_e32 v40, v170
	v_cvt_f32_f16_sdwa v41, v170 dst_sel:DWORD dst_unused:UNUSED_PAD src0_sel:WORD_1
	v_cvt_f32_f16_e32 v42, v171
	v_cvt_f32_f16_sdwa v43, v171 dst_sel:DWORD dst_unused:UNUSED_PAD src0_sel:WORD_1
	v_cvt_f32_f16_e32 v44, v172
	v_cvt_f32_f16_sdwa v45, v172 dst_sel:DWORD dst_unused:UNUSED_PAD src0_sel:WORD_1
	v_cvt_f32_f16_e32 v46, v173
	v_cvt_f32_f16_sdwa v47, v173 dst_sel:DWORD dst_unused:UNUSED_PAD src0_sel:WORD_1
	ds_write_b128 v34, v[40:43]
	ds_write_b128 v34, v[44:47] offset:16
	s_add_i32 s26, s26, 16
	s_waitcnt lgkmcnt(0)
	s_barrier
	s_cmpk_lg_i32 s26, 0x1100
	s_cbranch_scc1 .Lscan_loop
	s_waitcnt vmcnt(0)
	s_branch .LBB0_155
